# attention K/V tiles staged by LDS-DMA into the padded tile image (no VGPR round trip / ds_write_b128), DMA issued after the QK fragment reads; on top of v_c3
# baseline (speedup 1.0000x reference)
; __device__ __forceinline__ int fresh_lane() { int l; asm volatile("v_mbcnt_lo_u32_b32 %0, -1, 0\n\tv_mbcnt_hi_u32_b32 %0, -1, %0" : "=v"(l)); return l; }
; #define LAS __attribute__((address_space(3)))
; __device__ __forceinline__ void attn_phase(LAS unsigned char* lds, const bf16* PROJ, bf16* MIX, const float* lq1, const float* lk1, const float* lq2, const float* lk2,
;                                            const float* norm_g, float lambda_init, int G, int wave_s) {
;     int tid_ = wave_s * 64 + fresh_lane(); asm volatile("" : "+v"(tid_)); const int tid = tid_, lane = tid & 63, w = __builtin_amdgcn_readfirstlane(tid >> 6), q4 = lane >> 4, l15 = lane & 15, mi = w >> 2, wq = w & 3;
;     float lam;
;     { float s1 = lq1[lane] * lk1[lane] + lq1[lane + 64] * lk1[lane + 64], s2 = lq2[lane] * lk2[lane] + lq2[lane + 64] * lk2[lane + 64];
;       s1 = wave_sum(s1); s2 = wave_sum(s2); lam = expf(s1) - expf(s2) + lambda_init; }
;     LAS unsigned char* K0 = lds; LAS unsigned char* K1 = lds + 17408; LAS unsigned char* VT = lds + 34816; LAS unsigned char* XCH = lds;
;     LAS unsigned char* Kmine = mi ? K1 : K0;
;     const LAS unsigned char* vtr0 = VT + (4 * q4 + (l15 >> 2)) * 544 + (l15 & 3) * 8;
;     const float c1 = 0.08838834764831845f * LOG2E;
;     unsigned offK[2], offV[4];
; #pragma unroll
;     for (int j = 0; j < 2; ++j) { const int c = tid + 512 * j; offK[j] = (unsigned)((c >> 4) * PLD + 4096 + 8 * (c & 15)) * 2u; }
; #pragma unroll
;     for (int j = 0; j < 4; ++j) { const int c = tid + 512 * j; offV[j] = (unsigned)((c >> 5) * PLD + 5120 + 8 * (c & 31)) * 2u; }
;     for (int u0 = blockIdx.x; u0 < 256; u0 += G) {
;         const int u = (G == 256) ? (((u0 & 7) << 5) | (u0 >> 3)) : u0;
;         const int b = u >> 6, h = (u >> 4) & 3, p = u & 15;
;         const float sl2 = exp2f(-2.0f * (float)(h + 1)) * LOG2E;
;         const bf16* base = PROJ + (size_t)b * SEQ * PLD;
;         for (int half = 0; half < 2; ++half) {
;             const int qb = half ? 31 - p : p;
;             const int qloc = 16 * wq + l15;
;             bf16x8 qf[4];
;             { const bf16* qp = base + (size_t)(64 * qb + qloc) * PLD + 3072 + h * 256 + mi * 128 + 8 * q4;
.LBB0_879:
	s_or_b64 exec, exec, s[10:11]
	s_load_dwordx8 s[40:47], s[8:9], 0xe8
	v_readlane_b32 s10, v254, 57
	v_readlane_b32 s11, v254, 58
	s_lshl_b32 s80, s10, 7
	s_lshl_b64 s[10:11], s[80:81], 2
	s_waitcnt lgkmcnt(0)
	s_add_u32 s16, s40, s10
	v_mbcnt_lo_u32_b32 v0, -1, 0
	v_mbcnt_hi_u32_b32 v0, -1, v0
	s_addc_u32 s17, s41, s11
	v_add_u32_e32 v2, s89, v0
	s_add_u32 s14, s42, s10
	v_and_b32_e32 v3, 63, v2
	v_lshlrev_b32_e32 v0, 2, v3
	s_addc_u32 s15, s43, s11
	global_load_dword v4, v0, s[16:17]
	global_load_dword v5, v0, s[14:15]
	global_load_dword v6, v0, s[16:17] offset:256
	global_load_dword v7, v0, s[14:15] offset:256
	s_add_u32 s12, s44, s10
	s_addc_u32 s13, s45, s11
	s_add_u32 s10, s46, s10
	s_addc_u32 s11, s47, s11
	v_readfirstlane_b32 s18, v2
	s_andn2_b64 vcc, exec, s[86:87]
	s_waitcnt vmcnt(0)
	v_mul_f32_e32 v6, v6, v7
	v_fmac_f32_e32 v6, v4, v5
	global_load_dword v4, v0, s[12:13]
	global_load_dword v5, v0, s[10:11]
	global_load_dword v7, v0, s[12:13] offset:256
	s_nop 0
	global_load_dword v0, v0, s[10:11] offset:256
	s_waitcnt vmcnt(0)
	v_mul_f32_e32 v0, v7, v0
	v_fmac_f32_e32 v0, v4, v5
	v_add_f32_dpp v4, v6, v6 row_ror:8 row_mask:0xf bank_mask:0xf bound_ctrl:1
	s_nop 0
	v_add_f32_dpp v0, v0, v0 row_ror:8 row_mask:0xf bank_mask:0xf bound_ctrl:1
	v_add_f32_dpp v4, v4, v4 row_ror:4 row_mask:0xf bank_mask:0xf bound_ctrl:1
	s_nop 0
	v_add_f32_dpp v0, v0, v0 row_ror:4 row_mask:0xf bank_mask:0xf bound_ctrl:1
	v_add_f32_dpp v4, v4, v4 row_ror:2 row_mask:0xf bank_mask:0xf bound_ctrl:1
	s_nop 0
	v_add_f32_dpp v0, v0, v0 row_ror:2 row_mask:0xf bank_mask:0xf bound_ctrl:1
	v_add_f32_dpp v4, v4, v4 row_ror:1 row_mask:0xf bank_mask:0xf bound_ctrl:1
	v_mov_b32_e32 v5, v4
	s_nop 1
	v_permlane16_swap_b32_e32 v4, v5
	v_add_f32_dpp v0, v0, v0 row_ror:1 row_mask:0xf bank_mask:0xf bound_ctrl:1
	v_add_f32_e32 v5, v4, v5
	v_mov_b32_e32 v4, v0
	s_nop 1
	v_permlane16_swap_b32_e32 v0, v4
	v_add_f32_e32 v0, v0, v4
	v_mov_b32_e32 v6, v5
	v_mov_b32_e32 v4, v0
	s_nop 0
	v_permlane32_swap_b32_e32 v5, v6
	v_permlane32_swap_b32_e32 v0, v4
	s_cbranch_vccnz .LBB0_906
	s_load_dwordx2 s[8:9], s[8:9], 0x108
	v_readlane_b32 s10, v254, 57
	v_readlane_b32 s11, v254, 58
	s_lshl_b32 s80, s10, 8
	v_lshrrev_b32_e32 v7, 4, v3
	s_lshl_b64 s[10:11], s[80:81], 2
	s_waitcnt lgkmcnt(0)
	s_add_u32 s8, s8, s10
	v_lshlrev_b32_e32 v9, 2, v7
	v_bfe_u32 v10, v2, 2, 2
	s_addc_u32 s9, s9, s11
	v_readlane_b32 s10, v254, 53
	v_or_b32_e32 v10, v9, v10
	v_lshlrev_b32_e32 v11, 3, v2
	s_cmp_eq_u32 s10, 1
	v_mul_u32_u24_e32 v10, 0x220, v10
	v_and_b32_e32 v12, 24, v11
	s_cselect_b64 vcc, -1, 0
	v_add3_u32 v162, 0, v10, v12
	v_mov_b32_e32 v10, 0x3f0e59d4
	v_mov_b32_e32 v12, 0x3eb60549
	v_cndmask_b32_e32 v10, v10, v12, vcc
	v_add_u32_e32 v12, 0x600, v2
	v_ashrrev_i32_e32 v12, 5, v12
	s_movk_i32 s16, 0x1800
	v_and_b32_e32 v14, 0xf8, v11
	v_mul_lo_u32 v13, v12, s16
	v_or_b32_e32 v14, 0x1400, v14
	v_add_lshl_u32 v138, v13, v14, 1
	v_add_u32_e32 v13, 0x400, v2
	v_ashrrev_i32_e32 v13, 5, v13
	v_mul_lo_u32 v15, v13, s16
	v_add_lshl_u32 v140, v15, v14, 1
	v_add_u32_e32 v15, 0x200, v2
	v_ashrrev_i32_e32 v16, 5, v15
	s_ashr_i32 s21, s18, 8
	v_mul_lo_u32 v17, v16, s16
	v_readlane_b32 s11, v254, 54
	s_cmpk_eq_i32 s37, 0x100
	v_add_lshl_u32 v142, v17, v14, 1
	v_ashrrev_i32_e32 v17, 5, v2
	s_cselect_b64 s[10:11], -1, 0
	s_lshr_b32 s19, s18, 2
	s_lshl_b32 s12, s21, 7
	v_mul_lo_u32 v18, v17, s16
	s_and_b32 s20, s19, 48
	s_ashr_i32 s13, s12, 31
	s_add_i32 s26, 0, 0x19800
	v_add_lshl_u32 v144, v14, v18, 1
	v_ashrrev_i32_e32 v14, 4, v15
	v_and_b32_e32 v11, 0x78, v11
	v_add_f32_e32 v5, v5, v6
	s_cmpk_lt_u32 s18, 0x100
	v_mul_lo_u32 v15, v14, s16
	v_or_b32_e32 v11, 0x1000, v11
	v_mul_f32_e32 v6, 0x3fb8aa3b, v5
	s_mov_b32 s18, 0x3fb8aa3b
	v_add_lshl_u32 v146, v15, v11, 1
	v_ashrrev_i32_e32 v15, 4, v2
	v_fma_f32 v19, v5, s18, -v6
	v_rndne_f32_e32 v20, v6
	v_add_f32_e32 v0, v0, v4
	v_mul_lo_u32 v18, v15, s16
	v_fmac_f32_e32 v19, 0x32a5705f, v5
	v_sub_f32_e32 v6, v6, v20
	v_mul_f32_e32 v4, 0x3fb8aa3b, v0
	v_add_f32_e32 v6, v6, v19
	v_add_lshl_u32 v148, v11, v18, 1
	v_fma_f32 v11, v0, s18, -v4
	v_rndne_f32_e32 v18, v4
	v_exp_f32_e32 v6, v6
	v_cvt_i32_f32_e32 v19, v20
	v_fmac_f32_e32 v11, 0x32a5705f, v0
	v_sub_f32_e32 v4, v4, v18
	v_add_f32_e32 v4, v4, v11
	s_cselect_b64 s[14:15], -1, 0
	v_exp_f32_e32 v4, v4
	v_cvt_i32_f32_e32 v11, v18
	s_and_b64 s[16:17], s[14:15], exec
	s_mov_b32 s18, 0xc2ce8ed0
	v_ldexp_f32 v6, v6, v19
	v_cmp_ngt_f32_e32 vcc, s18, v5
	s_mov_b32 s17, 0x42b17218
	v_ldexp_f32 v4, v4, v11
	v_cndmask_b32_e32 v6, 0, v6, vcc
	v_cmp_nlt_f32_e32 vcc, s17, v5
	v_readlane_b32 s16, v254, 34
	s_cselect_b32 s16, 0, s16
	v_cndmask_b32_e32 v5, v218, v6, vcc
	v_cmp_ngt_f32_e32 vcc, s18, v0
	v_readlane_b32 s18, v254, 36
	v_and_b32_e32 v8, 15, v2
	v_cndmask_b32_e32 v4, 0, v4, vcc
	v_cmp_nlt_f32_e32 vcc, s17, v0
	v_readlane_b32 s17, v254, 35
	v_lshl_add_u32 v170, v3, 4, 0
	v_cndmask_b32_e32 v0, v218, v4, vcc
	v_lshlrev_b32_e32 v4, 4, v2
	v_sub_f32_e32 v0, v5, v0
	v_and_b32_e32 v5, 0xf0, v4
	v_and_b32_e32 v4, 0x1f0, v4
	v_add_u32_e32 v165, 0, v4
	v_add_u32_e32 v169, s26, v4
	v_mov_b32_e32 v4, s16
	s_cselect_b32 s16, s17, s18
	v_add_u32_e32 v164, 0, v5
	v_add_u32_e32 v167, s17, v5
	v_add_u32_e32 v168, s18, v5
	v_and_b32_e32 v5, 48, v2
	v_mov_b32_e32 v2, s16
	v_mad_u32_u24 v6, v8, s5, v2
	v_and_b32_e32 v2, 48, v3
	v_mov_b32_e32 v3, v1
	v_or_b32_e32 v163, s20, v8
	v_lshl_add_u64 v[154:155], s[8:9], 0, v[2:3]
	v_or_b32_e32 v2, 2, v9
	v_cmp_gt_u32_e64 s[44:45], v2, v163
	v_or_b32_e32 v2, 3, v9
	v_cmp_gt_u32_e64 s[46:47], v2, v163
	v_or_b32_e32 v2, 16, v9
	v_cmp_gt_u32_e64 s[48:49], v2, v163
	v_or_b32_e32 v2, 17, v9
; #define LAS __attribute__((address_space(3)))
; __device__ __forceinline__ void attn_phase(LAS unsigned char* lds, const bf16* PROJ, bf16* MIX, const float* lq1, const float* lk1, const float* lq2, const float* lk2,
;                                            const float* norm_g, float lambda_init, int G, int wave_s) {
;     ...
;     const LAS unsigned char* vtr0 = VT + (4 * q4 + (l15 >> 2)) * 544 + (l15 & 3) * 8;
;     const float c1 = 0.08838834764831845f * LOG2E;
;     unsigned offK[2], offV[4];
; #pragma unroll
;     for (int j = 0; j < 2; ++j) { const int c = tid + 512 * j; offK[j] = (unsigned)((c >> 4) * PLD + 4096 + 8 * (c & 15)) * 2u; }
; #pragma unroll
;     for (int j = 0; j < 4; ++j) { const int c = tid + 512 * j; offV[j] = (unsigned)((c >> 5) * PLD + 5120 + 8 * (c & 31)) * 2u; }
;     for (int u0 = blockIdx.x; u0 < 256; u0 += G) {
;         const int u = (G == 256) ? (((u0 & 7) << 5) | (u0 >> 3)) : u0;
;         const int b = u >> 6, h = (u >> 4) & 3, p = u & 15;
;         const float sl2 = exp2f(-2.0f * (float)(h + 1)) * LOG2E;
;         const bf16* base = PROJ + (size_t)b * SEQ * PLD;
;         for (int half = 0; half < 2; ++half) {
;             const int qb = half ? 31 - p : p;
;             const int qloc = 16 * wq + l15;
;             bf16x8 qf[4];
;             { const bf16* qp = base + (size_t)(64 * qb + qloc) * PLD + 3072 + h * 256 + mi * 128 + 8 * q4;
; #pragma unroll
;               for (int sk = 0; sk < 4; ++sk) qf[sk] = *(const bf16x8*)(qp + 32 * sk); }
;             f32x4 O[16];
; #pragma unroll
;             for (int mt = 0; mt < 16; ++mt) O[mt] = (f32x4){0.f, 0.f, 0.f, 0.f};
;             float m_run = -1e30f, l_part = 0.f;
;             v4u rk0[2], rk1[2], rv[4];
;     ...
;                     for (int r = 0; r < 4; ++r) { const int kl = 16 * t16 + 4 * q4 + r; float v = fmaf(s[t16][r], c1, fmaf(sl2, (float)(16 * t16 + r), nb));
;                         if (diag && kl > qloc) v = -1e30f; s[t16][r] = v; mx = fmaxf(mx, v); }
	v_cmp_gt_u32_e64 s[50:51], v2, v163
	v_or_b32_e32 v2, 18, v9
	v_cmp_gt_u32_e64 s[52:53], v2, v163
	v_or_b32_e32 v2, 19, v9
	v_cmp_gt_u32_e64 s[54:55], v2, v163
	v_or_b32_e32 v2, 32, v9
	v_cmp_gt_u32_e64 s[56:57], v2, v163
	v_or_b32_e32 v2, 33, v9
	v_cmp_gt_u32_e64 s[58:59], v2, v163
	v_or_b32_e32 v2, 34, v9
	v_cmp_gt_u32_e64 s[60:61], v2, v163
	v_or_b32_e32 v2, 35, v9
	v_cmp_gt_u32_e64 s[62:63], v2, v163
	v_or_b32_e32 v2, 48, v9
	v_cmp_gt_u32_e64 s[64:65], v2, v163
	v_or_b32_e32 v2, 49, v9
	v_add_f32_e32 v150, v10, v0
	v_lshlrev_b32_e32 v0, 3, v7
	s_cmp_eq_u32 s21, 1
	s_movk_i32 s8, 0x220
	v_cmp_gt_u32_e64 s[66:67], v2, v163
	v_or_b32_e32 v2, 50, v9
	v_mad_u32_u24 v4, v8, s5, v4
	s_cselect_b64 s[16:17], -1, 0
	v_mul_lo_u32 v174, v17, s8
	v_mul_lo_u32 v175, v16, s8
	v_mul_lo_u32 v176, v13, s8
	v_mul_lo_u32 v177, v12, s8
	v_cmp_gt_u32_e64 s[68:69], v2, v163
	v_or_b32_e32 v2, 51, v9
	s_lshl_b32 s8, s19, 10
	v_lshl_add_u64 v[156:157], s[0:1], 0, v[0:1]
	v_readlane_b32 s0, v253, 0
	s_mov_b32 s2, 0x3fb8aa3b
	s_mov_b32 s34, 0xc2ce8ed0
	s_mov_b32 s35, 0x42b17218
	v_cvt_f32_ubyte0_e32 v166, v9
	v_mov_b32_e32 v151, v150
	v_mov_b32_e32 v152, v150
	v_mov_b32_e32 v153, v150
	v_sub_f32_e32 v171, 1.0, v10
	v_mov_b32_e32 v149, v1
	v_mov_b32_e32 v147, v1
	v_mov_b32_e32 v145, v1
	v_mov_b32_e32 v143, v1
	v_mov_b32_e32 v141, v1
	v_mov_b32_e32 v139, v1
	v_mul_lo_u32 v172, v15, s5
	v_mul_lo_u32 v173, v14, s5
	v_cmp_gt_u32_e64 s[40:41], v9, v163
	v_cmp_ge_u32_e64 s[42:43], v9, v163
	v_cmp_gt_u32_e64 s[70:71], v2, v163
	v_add_u32_e32 v178, 0x1bb00, v162
	v_add_u32_e32 v179, 0x1dd00, v162
	v_add_u32_e32 v180, 0x1ff00, v162
	v_add_u32_e32 v181, 0x19920, v162
	v_add_u32_e32 v182, 0x1bb20, v162
	v_add_u32_e32 v183, 0x1dd20, v162
	v_add_u32_e32 v184, 0x1ff20, v162
	v_add_u32_e32 v185, 0x19940, v162
	v_add_u32_e32 v186, 0x1bb40, v162
	v_add_u32_e32 v187, 0x1dd40, v162
	v_add_u32_e32 v188, 0x1ff40, v162
	v_add_u32_e32 v189, 0x19960, v162
	v_add_u32_e32 v190, 0x1bb60, v162
	v_add_u32_e32 v191, 0x1dd60, v162
	v_add_u32_e32 v192, 0x1ff60, v162
	v_add_u32_e32 v193, 0x19980, v162
	v_add_u32_e32 v194, 0x1bb80, v162
	v_add_u32_e32 v195, 0x1dd80, v162
	v_add_u32_e32 v196, 0x1ff80, v162
	v_add_u32_e32 v197, 0x199a0, v162
	v_add_u32_e32 v198, 0x1bba0, v162
	v_add_u32_e32 v199, 0x1dda0, v162
	v_add_u32_e32 v200, 0x1ffa0, v162
	v_add_u32_e32 v201, 0x199c0, v162
	v_add_u32_e32 v202, 0x1bbc0, v162
	v_add_u32_e32 v203, 0x1ddc0, v162
	v_add_u32_e32 v204, 0x1ffc0, v162
	v_add_u32_e32 v205, 0x199e0, v162
	v_add_u32_e32 v206, 0x1bbe0, v162
	v_add_u32_e32 v207, 0x1dde0, v162
	v_add_u32_e32 v208, 0x1ffe0, v162
	s_lshl_b32 s72, s20, 10
	s_or_b32 s73, s8, 0x3c00
	v_lshlrev_b32_e32 v158, 1, v0
	v_add_u32_e32 v209, v4, v5
	v_add_u32_e32 v210, v6, v5
	v_mbcnt_lo_u32_b32 v82, -1, 0
	v_mbcnt_hi_u32_b32 v82, -1, v82
	v_add_u32_e32 v82, s89, v82
	v_mov_b32_e32 v96, 17
	v_mov_b32_e32 v97, 34
	v_mov_b32_e32 v98, 15
	v_mov_b32_e32 v99, 31
	v_mov_b32_e32 v100, 0x2000
	v_mov_b32_e32 v101, 0x2800
	v_mov_b32_e32 v83, v82
	v_subrev_u32_e32 v84, 0x880, v83
	v_cmp_gt_u32_e32 vcc, 0x880, v83
	v_cndmask_b32_e32 v84, v84, v83, vcc
	v_mul_u32_u24_e32 v85, 0xf0f1, v84
	v_lshrrev_b32_e32 v85, 20, v85
	v_lshrrev_b32_e32 v86, 1, v85
	v_cndmask_b32_e32 v85, v86, v85, vcc
	v_cndmask_b32_e32 v87, v97, v96, vcc
	v_mul_u32_u24_e32 v88, v85, v87
	v_sub_u32_e32 v88, v84, v88
	v_cndmask_b32_e32 v89, v99, v98, vcc
	v_min_u32_e32 v88, v88, v89
	v_cndmask_b32_e32 v89, v101, v100, vcc
	v_lshl_add_u32 v88, v88, 4, v89
	v_and_b32_e32 v86, 63, v85
	v_lshrrev_b32_e32 v87, 6, v85
	v_lshl_add_u32 v88, v87, 8, v88
	v_mul_u32_u24_e32 v86, 0x3000, v86
	v_add_u32_e32 v138, v86, v88
	v_add_u32_e32 v83, 512, v82
	v_subrev_u32_e32 v84, 0x880, v83
	v_cmp_gt_u32_e32 vcc, 0x880, v83
	v_cndmask_b32_e32 v84, v84, v83, vcc
	v_mul_u32_u24_e32 v85, 0xf0f1, v84
	v_lshrrev_b32_e32 v85, 20, v85
	v_lshrrev_b32_e32 v86, 1, v85
	v_cndmask_b32_e32 v85, v86, v85, vcc
	v_cndmask_b32_e32 v87, v97, v96, vcc
	v_mul_u32_u24_e32 v88, v85, v87
	v_sub_u32_e32 v88, v84, v88
	v_cndmask_b32_e32 v89, v99, v98, vcc
	v_min_u32_e32 v88, v88, v89
	v_cndmask_b32_e32 v89, v101, v100, vcc
	v_lshl_add_u32 v88, v88, 4, v89
	v_and_b32_e32 v86, 63, v85
	v_lshrrev_b32_e32 v87, 6, v85
	v_lshl_add_u32 v88, v87, 8, v88
	v_mul_u32_u24_e32 v86, 0x3000, v86
	v_add_u32_e32 v139, v86, v88
	v_add_u32_e32 v83, 1024, v82
	v_subrev_u32_e32 v84, 0x880, v83
	v_cmp_gt_u32_e32 vcc, 0x880, v83
	v_cndmask_b32_e32 v84, v84, v83, vcc
	v_mul_u32_u24_e32 v85, 0xf0f1, v84
	v_lshrrev_b32_e32 v85, 20, v85
	v_lshrrev_b32_e32 v86, 1, v85
; __device__ __forceinline__ void attn_phase(LAS unsigned char* lds, const bf16* PROJ, bf16* MIX, const float* lq1, const float* lk1, const float* lq2, const float* lk2,
;                                            const float* norm_g, float lambda_init, int G, int wave_s) {
;     ...
;     unsigned offK[2], offV[4];
; #pragma unroll
;     for (int j = 0; j < 2; ++j) { const int c = tid + 512 * j; offK[j] = (unsigned)((c >> 4) * PLD + 4096 + 8 * (c & 15)) * 2u; }
; #pragma unroll
;     for (int j = 0; j < 4; ++j) { const int c = tid + 512 * j; offV[j] = (unsigned)((c >> 5) * PLD + 5120 + 8 * (c & 31)) * 2u; }
;     for (int u0 = blockIdx.x; u0 < 256; u0 += G) {
;         const int u = (G == 256) ? (((u0 & 7) << 5) | (u0 >> 3)) : u0;
;         const int b = u >> 6, h = (u >> 4) & 3, p = u & 15;
;         const float sl2 = exp2f(-2.0f * (float)(h + 1)) * LOG2E;
;         const bf16* base = PROJ + (size_t)b * SEQ * PLD;
;         for (int half = 0; half < 2; ++half) {
;             const int qb = half ? 31 - p : p;
;             const int qloc = 16 * wq + l15;
;             bf16x8 qf[4];
;             { const bf16* qp = base + (size_t)(64 * qb + qloc) * PLD + 3072 + h * 256 + mi * 128 + 8 * q4;
; #pragma unroll
;               for (int sk = 0; sk < 4; ++sk) qf[sk] = *(const bf16x8*)(qp + 32 * sk); }
;             f32x4 O[16];
; #pragma unroll
;             for (int mt = 0; mt < 16; ++mt) O[mt] = (f32x4){0.f, 0.f, 0.f, 0.f};
;             float m_run = -1e30f, l_part = 0.f;
;             v4u rk0[2], rk1[2], rv[4];
	v_cndmask_b32_e32 v85, v86, v85, vcc
	v_cndmask_b32_e32 v87, v97, v96, vcc
	v_mul_u32_u24_e32 v88, v85, v87
	v_sub_u32_e32 v88, v84, v88
	v_cndmask_b32_e32 v89, v99, v98, vcc
	v_min_u32_e32 v88, v88, v89
	v_cndmask_b32_e32 v89, v101, v100, vcc
	v_lshl_add_u32 v88, v88, 4, v89
	v_and_b32_e32 v86, 63, v85
	v_lshrrev_b32_e32 v87, 6, v85
	v_lshl_add_u32 v88, v87, 8, v88
	v_mul_u32_u24_e32 v86, 0x3000, v86
	v_add_u32_e32 v140, v86, v88
	v_add_u32_e32 v83, 1536, v82
	v_subrev_u32_e32 v84, 0x880, v83
	v_cmp_gt_u32_e32 vcc, 0x880, v83
	v_cndmask_b32_e32 v84, v84, v83, vcc
	v_mul_u32_u24_e32 v85, 0xf0f1, v84
	v_lshrrev_b32_e32 v85, 20, v85
	v_lshrrev_b32_e32 v86, 1, v85
	v_cndmask_b32_e32 v85, v86, v85, vcc
	v_cndmask_b32_e32 v87, v97, v96, vcc
	v_mul_u32_u24_e32 v88, v85, v87
	v_sub_u32_e32 v88, v84, v88
	v_cndmask_b32_e32 v89, v99, v98, vcc
	v_min_u32_e32 v88, v88, v89
	v_cndmask_b32_e32 v89, v101, v100, vcc
	v_lshl_add_u32 v88, v88, 4, v89
	v_and_b32_e32 v86, 63, v85
	v_lshrrev_b32_e32 v87, 6, v85
	v_lshl_add_u32 v88, v87, 8, v88
	v_mul_u32_u24_e32 v86, 0x3000, v86
	v_add_u32_e32 v141, v86, v88
	v_add_u32_e32 v83, 2048, v82
	v_subrev_u32_e32 v84, 0x880, v83
	v_cmp_gt_u32_e32 vcc, 0x880, v83
	v_cndmask_b32_e32 v84, v84, v83, vcc
	v_mul_u32_u24_e32 v85, 0xf0f1, v84
	v_lshrrev_b32_e32 v85, 20, v85
	v_lshrrev_b32_e32 v86, 1, v85
	v_cndmask_b32_e32 v85, v86, v85, vcc
	v_cndmask_b32_e32 v87, v97, v96, vcc
	v_mul_u32_u24_e32 v88, v85, v87
	v_sub_u32_e32 v88, v84, v88
	v_cndmask_b32_e32 v89, v99, v98, vcc
	v_min_u32_e32 v88, v88, v89
	v_cndmask_b32_e32 v89, v101, v100, vcc
	v_lshl_add_u32 v88, v88, 4, v89
	v_and_b32_e32 v86, 63, v85
	v_lshrrev_b32_e32 v87, 6, v85
	v_lshl_add_u32 v88, v87, 8, v88
	v_mul_u32_u24_e32 v86, 0x3000, v86
	v_add_u32_e32 v142, v86, v88
	v_add_u32_e32 v83, 2560, v82
	v_subrev_u32_e32 v84, 0x880, v83
	v_cmp_gt_u32_e32 vcc, 0x880, v83
	v_cndmask_b32_e32 v84, v84, v83, vcc
	v_mul_u32_u24_e32 v85, 0xf0f1, v84
	v_lshrrev_b32_e32 v85, 20, v85
	v_lshrrev_b32_e32 v86, 1, v85
	v_cndmask_b32_e32 v85, v86, v85, vcc
	v_cndmask_b32_e32 v87, v97, v96, vcc
	v_mul_u32_u24_e32 v88, v85, v87
	v_sub_u32_e32 v88, v84, v88
	v_cndmask_b32_e32 v89, v99, v98, vcc
	v_min_u32_e32 v88, v88, v89
	v_cndmask_b32_e32 v89, v101, v100, vcc
	v_lshl_add_u32 v88, v88, 4, v89
	v_and_b32_e32 v86, 63, v85
	v_lshrrev_b32_e32 v87, 6, v85
	v_lshl_add_u32 v88, v87, 8, v88
	v_mul_u32_u24_e32 v86, 0x3000, v86
	v_add_u32_e32 v143, v86, v88
	v_add_u32_e32 v83, 3072, v82
	v_subrev_u32_e32 v84, 0x880, v83
	v_cmp_gt_u32_e32 vcc, 0x880, v83
	v_cndmask_b32_e32 v84, v84, v83, vcc
	v_mul_u32_u24_e32 v85, 0xf0f1, v84
	v_lshrrev_b32_e32 v85, 20, v85
	v_lshrrev_b32_e32 v86, 1, v85
	v_cndmask_b32_e32 v85, v86, v85, vcc
	v_cndmask_b32_e32 v87, v97, v96, vcc
	v_mul_u32_u24_e32 v88, v85, v87
	v_sub_u32_e32 v88, v84, v88
	v_cndmask_b32_e32 v89, v99, v98, vcc
	v_min_u32_e32 v88, v88, v89
	v_cndmask_b32_e32 v89, v101, v100, vcc
	v_lshl_add_u32 v88, v88, 4, v89
	v_and_b32_e32 v86, 63, v85
	v_lshrrev_b32_e32 v87, 6, v85
	v_lshl_add_u32 v88, v87, 8, v88
	v_mul_u32_u24_e32 v86, 0x3000, v86
	v_add_u32_e32 v144, v86, v88
	v_add_u32_e32 v83, 3584, v82
	v_subrev_u32_e32 v84, 0x880, v83
	v_cmp_gt_u32_e32 vcc, 0x880, v83
	v_cndmask_b32_e32 v84, v84, v83, vcc
	v_mul_u32_u24_e32 v85, 0xf0f1, v84
	v_lshrrev_b32_e32 v85, 20, v85
	v_lshrrev_b32_e32 v86, 1, v85
	v_cndmask_b32_e32 v85, v86, v85, vcc
	v_cndmask_b32_e32 v87, v97, v96, vcc
	v_mul_u32_u24_e32 v88, v85, v87
	v_sub_u32_e32 v88, v84, v88
	v_cndmask_b32_e32 v89, v99, v98, vcc
	v_min_u32_e32 v88, v88, v89
	v_cndmask_b32_e32 v89, v101, v100, vcc
	v_lshl_add_u32 v88, v88, 4, v89
	v_and_b32_e32 v86, 63, v85
	v_lshrrev_b32_e32 v87, 6, v85
	v_lshl_add_u32 v88, v87, 8, v88
	v_mul_u32_u24_e32 v86, 0x3000, v86
	v_add_u32_e32 v145, v86, v88
	v_add_u32_e32 v83, 4096, v82
	v_subrev_u32_e32 v84, 0x880, v83
	v_cmp_gt_u32_e32 vcc, 0x880, v83
	v_cndmask_b32_e32 v84, v84, v83, vcc
	v_mul_u32_u24_e32 v85, 0xf0f1, v84
	v_lshrrev_b32_e32 v85, 20, v85
	v_lshrrev_b32_e32 v86, 1, v85
	v_cndmask_b32_e32 v85, v86, v85, vcc
	v_cndmask_b32_e32 v87, v97, v96, vcc
	v_mul_u32_u24_e32 v88, v85, v87
	v_sub_u32_e32 v88, v84, v88
	v_cndmask_b32_e32 v89, v99, v98, vcc
	v_min_u32_e32 v88, v88, v89
	v_cndmask_b32_e32 v89, v101, v100, vcc
	v_lshl_add_u32 v88, v88, 4, v89
	v_and_b32_e32 v86, 63, v85
	v_lshrrev_b32_e32 v87, 6, v85
	v_lshl_add_u32 v88, v87, 8, v88
	v_mul_u32_u24_e32 v86, 0x3000, v86
	v_add_u32_e32 v146, v86, v88
	s_mov_b32 s76, s0
	v_readlane_b32 s1, v253, 1
	s_cmpk_lt_u32 s89, 0x100
	s_cbranch_scc1 .Lattn_prio_done
	s_setprio 1

; __device__ __forceinline__ void attn_phase(LAS unsigned char* lds, const bf16* PROJ, bf16* MIX, const float* lq1, const float* lk1, const float* lq2, const float* lk2,
;                                            const float* norm_g, float lambda_init, int G, int wave_s) {
;     ...
;             { const bf16* qp = base + (size_t)(64 * qb + qloc) * PLD + 3072 + h * 256 + mi * 128 + 8 * q4;
; #pragma unroll
;               for (int sk = 0; sk < 4; ++sk) qf[sk] = *(const bf16x8*)(qp + 32 * sk); }
;             f32x4 O[16];
; #pragma unroll
;             for (int mt = 0; mt < 16; ++mt) O[mt] = (f32x4){0.f, 0.f, 0.f, 0.f};
;             float m_run = -1e30f, l_part = 0.f;
;             v4u rk0[2], rk1[2], rv[4];
;     ...
;             ATT_LOAD(qb);
;             ATT_WRITE(0);
;             if (qb >= 1) ATT_LOAD(qb - 1);
;             __syncthreads();
.LBB0_884:
	s_and_b64 s[8:9], s[0:1], exec
	s_cselect_b32 s86, s77, s78
	s_lshl_b32 s85, s86, 6
	v_or_b32_e32 v0, s85, v163
	v_mul_u32_u24_e32 v0, 0x1800, v0
	v_lshlrev_b32_e32 v0, 1, v0
	v_lshl_add_u64 v[2:3], s[18:19], 0, v[0:1]
	v_lshl_add_u64 v[2:3], v[2:3], 0, s[80:81]
	v_lshl_add_u64 v[2:3], s[12:13], 1, v[2:3]
	v_mov_b32_e32 v159, v1
	v_lshl_add_u64 v[2:3], v[2:3], 0, v[158:159]
	s_mov_b64 s[8:9], 0x1800
	v_lshl_add_u64 v[4:5], v[2:3], 0, s[8:9]
	s_mul_i32 s8, s86, 0xc0000
	v_add_co_u32_e32 v2, vcc, s75, v2
	s_add_u32 s20, s79, s8
	s_nop 0
	v_addc_co_u32_e32 v3, vcc, 0, v3, vcc
	s_addc_u32 s21, s82, 0
	global_load_dwordx4 v[66:69], v[4:5], off offset:64
	global_load_dwordx4 v[70:73], v[4:5], off offset:128
	global_load_dwordx4 v[74:77], v[2:3], off offset:2048
	global_load_dwordx4 v[78:81], v[4:5], off offset:192
	s_lshl_b32 s100, s89, 4
	s_mov_b32 m0, s100
	s_nop 0
	global_load_lds_dwordx4 v138, s[20:21]
	s_add_i32 m0, s100, 0x2000
	s_nop 0
	global_load_lds_dwordx4 v139, s[20:21]
	s_add_i32 m0, s100, 0x4000
	s_nop 0
	global_load_lds_dwordx4 v140, s[20:21]
	s_add_i32 m0, s100, 0x6000
	s_nop 0
	global_load_lds_dwordx4 v141, s[20:21]
	s_add_i32 m0, s100, 0x8000
	s_nop 0
	global_load_lds_dwordx4 v142, s[20:21]
	s_add_i32 m0, s100, 0xa000
	s_nop 0
	global_load_lds_dwordx4 v143, s[20:21]
	s_add_i32 m0, s100, 0xc000
	s_nop 0
	global_load_lds_dwordx4 v144, s[20:21]
	s_add_i32 m0, s100, 0xe000
	s_nop 0
	global_load_lds_dwordx4 v145, s[20:21]
	s_cmpk_ge_u32 s89, 0x100
	s_cbranch_scc1 .Lattn_dma_1
	s_add_i32 m0, s100, 0x10000
	s_nop 0
	global_load_lds_dwordx4 v146, s[20:21]
.Lattn_dma_1:
.LBB0_886:
	v_mov_b32_e32 v2, v1
	v_mov_b32_e32 v3, v1
	s_xor_b64 s[20:21], s[0:1], -1
	s_add_i32 s87, s86, -2
	v_mov_b32_e32 v0, v1
	v_mov_b64_e32 v[16:17], v[2:3]
	v_mov_b64_e32 v[24:25], v[2:3]
	v_mov_b64_e32 v[28:29], v[2:3]
	v_mov_b64_e32 v[32:33], v[2:3]
	v_mov_b64_e32 v[36:37], v[2:3]
	v_mov_b64_e32 v[40:41], v[2:3]
	v_mov_b64_e32 v[44:45], v[2:3]
	v_mov_b64_e32 v[48:49], v[2:3]
	v_mov_b64_e32 v[52:53], v[2:3]
	v_mov_b64_e32 v[56:57], v[2:3]
	v_mov_b64_e32 v[60:61], v[2:3]
	v_mov_b64_e32 v[64:65], v[2:3]
	v_mov_b64_e32 v[20:21], v[2:3]
	v_mov_b64_e32 v[12:13], v[2:3]
	v_mov_b64_e32 v[8:9], v[2:3]
	s_add_u32 s0, s83, s8
	v_mov_b64_e32 v[14:15], v[0:1]
	v_mov_b64_e32 v[22:23], v[0:1]
	v_mov_b64_e32 v[26:27], v[0:1]
	v_mov_b64_e32 v[30:31], v[0:1]
	v_mov_b64_e32 v[34:35], v[0:1]
	v_mov_b64_e32 v[38:39], v[0:1]
	v_mov_b64_e32 v[42:43], v[0:1]
	v_mov_b64_e32 v[46:47], v[0:1]
	v_mov_b64_e32 v[50:51], v[0:1]
	v_mov_b64_e32 v[54:55], v[0:1]
	v_mov_b64_e32 v[58:59], v[0:1]
	v_mov_b64_e32 v[62:63], v[0:1]
	v_mov_b64_e32 v[18:19], v[0:1]
	v_mov_b64_e32 v[10:11], v[0:1]
	v_mov_b64_e32 v[6:7], v[0:1]
	v_mov_b64_e32 v[4:5], v[2:3]
	s_addc_u32 s1, s84, 0
	s_mov_b32 s88, 0
	v_mov_b32_e32 v225, 0
	v_mov_b32_e32 v226, 0xf149f2ca
	v_mov_b32_e32 v224, v163
	v_mov_b64_e32 v[2:3], v[0:1]
	s_waitcnt vmcnt(0) lgkmcnt(0)
	s_barrier
	s_branch .LBB0_889

; __device__ __forceinline__ float xor16_max(float v) { const auto r = __builtin_amdgcn_permlane16_swap(__float_as_uint(v), __float_as_uint(v), false, false); return fmaxf(__uint_as_float(r[0]), __uint_as_float(r[1])); }
; __device__ __forceinline__ float xor32_max(float v) { const auto r = __builtin_amdgcn_permlane32_swap(__float_as_uint(v), __float_as_uint(v), false, false); return fmaxf(__uint_as_float(r[0]), __uint_as_float(r[1])); }
; #define LAS __attribute__((address_space(3)))
; #define ATT_LDK(dst_, t16_) do { _Pragma("unroll") for (int sk = 0; sk < 4; ++sk) dst_[sk] = *(const LAS bf16x8*)(kb_ + (16 * (t16_) + l15) * 272 + (32 * sk + 8 * q4) * 2); } while (0)
; #define ATT_QK(src_, t16_) do { f32x4 acc = (f32x4){0.f, 0.f, 0.f, 0.f}; _Pragma("unroll") for (int sk = 0; sk < 4; ++sk) acc = mfma16(src_[sk], qf[sk], acc); s[t16_] = acc; } while (0)
; __device__ __forceinline__ void attn_phase(LAS unsigned char* lds, const bf16* PROJ, bf16* MIX, const float* lq1, const float* lk1, const float* lq2, const float* lk2,
;                                            const float* norm_g, float lambda_init, int G, int wave_s) {
;     ...
;               { const int kt = kt0;
;                 if (kt < qb) { ATT_WRITE(69632); if (kt + 1 < qb) ATT_LOAD(qb - (kt + 2)); }
;                 const LAS unsigned char* kb_ = Kmine; const LAS unsigned char* vb_ = vtr0;
;                 f32x4 s[4];
;                 { bf16x8 kfa[4], kfb[4];
;                   ATT_LDK(kfa, 0); ATT_LDK(kfb, 1); ATT_SB(); ATT_QK(kfa, 0); ATT_LDK(kfa, 2); ATT_SB(); ATT_QK(kfb, 1); ATT_LDK(kfb, 3); ATT_SB(); ATT_QK(kfa, 2); ATT_QK(kfb, 3); }
;                 const int dq = 64 * kt + qloc; const bool diag = (kt == 0);
;                 const float nb = -sl2 * ((float)dq - q4f);
;                 float mx = -1e30f;
; #pragma unroll
;                 for (int t16 = 0; t16 < 4; ++t16)
; #pragma unroll
;                     for (int r = 0; r < 4; ++r) { const int kl = 16 * t16 + 4 * q4 + r; float v = fmaf(s[t16][r], c1, fmaf(sl2, (float)(16 * t16 + r), nb));
;                         if (diag && kl > qloc) v = -1e30f; s[t16][r] = v; mx = fmaxf(mx, v); }
;                 mx = xor32_max(xor16_max(mx));
;                 const bool resc = __builtin_amdgcn_ballot_w64(mx > m_run) != 0ull;
;                 const float mn = fmaxf(m_run, mx), alpha = __builtin_amdgcn_exp2f(m_run - mn); m_run = mn;
.LBB0_892:
	ds_read_b128 v[114:117], v209
	ds_read_b128 v[118:121], v209 offset:64
	ds_read_b128 v[122:125], v209 offset:128
	ds_read_b128 v[126:129], v209 offset:192
	ds_read_b128 v[130:133], v209 offset:4352
	ds_read_b128 v[134:137], v209 offset:4416
	ds_read_b128 v[228:231], v209 offset:4480
	ds_read_b128 v[232:235], v209 offset:4544
	s_waitcnt lgkmcnt(7)
	v_mfma_f32_16x16x32_bf16 v[114:117], v[114:117], v[74:77], 0
	s_waitcnt lgkmcnt(6)
	v_mfma_f32_16x16x32_bf16 v[114:117], v[118:121], v[66:69], v[114:117]
	s_waitcnt lgkmcnt(5)
	v_mfma_f32_16x16x32_bf16 v[114:117], v[122:125], v[70:73], v[114:117]
	s_waitcnt lgkmcnt(4)
	v_mfma_f32_16x16x32_bf16 v[114:117], v[126:129], v[78:81], v[114:117]
	ds_read_b128 v[118:121], v209 offset:8704
	ds_read_b128 v[122:125], v209 offset:8768
	ds_read_b128 v[126:129], v209 offset:8832
	ds_read_b128 v[236:239], v209 offset:8896
	s_waitcnt lgkmcnt(7)
	v_mfma_f32_16x16x32_bf16 v[130:133], v[130:133], v[74:77], 0
	s_waitcnt lgkmcnt(6)
	v_mfma_f32_16x16x32_bf16 v[130:133], v[134:137], v[66:69], v[130:133]
	s_waitcnt lgkmcnt(5)
	v_mfma_f32_16x16x32_bf16 v[130:133], v[228:231], v[70:73], v[130:133]
	s_waitcnt lgkmcnt(4)
	v_mfma_f32_16x16x32_bf16 v[134:137], v[232:235], v[78:81], v[130:133]
	s_nop 5
	ds_read_b128 v[130:133], v209 offset:13056
	ds_read_b128 v[228:231], v209 offset:13120
	ds_read_b128 v[232:235], v209 offset:13184
	ds_read_b128 v[240:243], v209 offset:13248
	s_cmp_ge_u32 s88, s86
	s_cbranch_scc1 .Lattn_dl1
	s_add_u32 s26, s0, 0x180000
	s_addc_u32 s27, s1, 0
	s_lshl_b32 s100, s89, 4
	s_add_i32 s100, s100, 0x11000
	s_mov_b32 m0, s100
	s_nop 0
	global_load_lds_dwordx4 v138, s[26:27]
	s_add_i32 m0, s100, 0x2000
	s_nop 0
	global_load_lds_dwordx4 v139, s[26:27]
	s_add_i32 m0, s100, 0x4000
	s_nop 0
	global_load_lds_dwordx4 v140, s[26:27]
	s_add_i32 m0, s100, 0x6000
	s_nop 0
	global_load_lds_dwordx4 v141, s[26:27]
	s_add_i32 m0, s100, 0x8000
	s_nop 0
	global_load_lds_dwordx4 v142, s[26:27]
	s_add_i32 m0, s100, 0xa000
	s_nop 0
	global_load_lds_dwordx4 v143, s[26:27]
	s_add_i32 m0, s100, 0xc000
	s_nop 0
	global_load_lds_dwordx4 v144, s[26:27]
	s_add_i32 m0, s100, 0xe000
	s_nop 0
	global_load_lds_dwordx4 v145, s[26:27]
	s_cmpk_ge_u32 s89, 0x100
	s_cbranch_scc1 .Lattn_dma_2
	s_add_i32 m0, s100, 0x10000
	s_nop 0
	global_load_lds_dwordx4 v146, s[26:27]
.Lattn_dma_2:
.Lattn_dl1:
	s_waitcnt lgkmcnt(7)
	v_mfma_f32_16x16x32_bf16 v[118:121], v[118:121], v[74:77], 0
	v_cvt_f32_u32_e32 v0, v224
	s_cmp_eq_u32 s88, 0
	s_cselect_b64 s[26:27], -1, 0
	s_waitcnt lgkmcnt(6)
	v_mfma_f32_16x16x32_bf16 v[118:121], v[122:125], v[66:69], v[118:121]
	v_sub_f32_e32 v0, v0, v166
	s_and_b64 vcc, s[26:27], s[40:41]
	s_waitcnt lgkmcnt(5)
	v_mfma_f32_16x16x32_bf16 v[118:121], v[126:129], v[70:73], v[118:121]
	v_mul_f32_e64 v126, v0, -v211
	v_fma_f32 v127, 0, v211, v126
	v_fmac_f32_e32 v127, 0x3e0293ee, v114
	v_fma_f32 v0, v0, -v211, v211
	s_waitcnt lgkmcnt(3)
	v_mfma_f32_16x16x32_bf16 v[122:125], v[130:133], v[74:77], 0
	v_cndmask_b32_e32 v130, v127, v219, vcc
	v_fmac_f32_e32 v0, 0x3e0293ee, v115
	s_and_b64 vcc, s[26:27], s[42:43]
	v_fma_f32 v114, 2.0, v211, v126
	v_cndmask_b32_e32 v131, v0, v219, vcc
	v_fmac_f32_e32 v114, 0x3e0293ee, v116
	s_and_b64 vcc, s[26:27], s[44:45]
	v_cndmask_b32_e32 v132, v114, v219, vcc
	v_fmamk_f32 v114, v211, 0x40400000, v126
	v_fmac_f32_e32 v114, 0x3e0293ee, v117
	s_and_b64 vcc, s[26:27], s[46:47]
	v_cndmask_b32_e32 v133, v114, v219, vcc
	v_fmamk_f32 v114, v211, 0x41800000, v126
	v_fmac_f32_e32 v114, 0x3e0293ee, v134
	s_and_b64 vcc, s[26:27], s[48:49]
	v_cndmask_b32_e32 v134, v114, v219, vcc
	v_fmamk_f32 v114, v211, 0x41880000, v126
	v_fmac_f32_e32 v114, 0x3e0293ee, v135
	s_and_b64 vcc, s[26:27], s[50:51]
	v_cndmask_b32_e32 v135, v114, v219, vcc
	v_fmamk_f32 v114, v211, 0x41900000, v126
	v_mfma_f32_16x16x32_bf16 v[118:121], v[236:239], v[78:81], v[118:121]
	v_fmac_f32_e32 v114, 0x3e0293ee, v136
	s_and_b64 vcc, s[26:27], s[52:53]
	v_cndmask_b32_e32 v136, v114, v219, vcc
	s_waitcnt lgkmcnt(2)
	v_mfma_f32_16x16x32_bf16 v[122:125], v[228:231], v[66:69], v[122:125]
	v_fmamk_f32 v114, v211, 0x41980000, v126
	v_fmac_f32_e32 v114, 0x3e0293ee, v137
	s_and_b64 vcc, s[26:27], s[54:55]
	v_cndmask_b32_e32 v137, v114, v219, vcc
	v_fmamk_f32 v114, v211, 0x42000000, v126
	s_waitcnt lgkmcnt(1)
	v_mfma_f32_16x16x32_bf16 v[122:125], v[232:235], v[70:73], v[122:125]
	v_fmac_f32_e32 v114, 0x3e0293ee, v118
	s_and_b64 vcc, s[26:27], s[56:57]
	v_cndmask_b32_e32 v227, v114, v219, vcc
	v_fmamk_f32 v114, v211, 0x42040000, v126
	v_fmac_f32_e32 v114, 0x3e0293ee, v119
	s_and_b64 vcc, s[26:27], s[58:59]
	v_cndmask_b32_e32 v229, v114, v219, vcc
	v_fmamk_f32 v114, v211, 0x42080000, v126
	s_waitcnt lgkmcnt(0)
	v_mfma_f32_16x16x32_bf16 v[122:125], v[240:243], v[78:81], v[122:125]
	v_fmac_f32_e32 v114, 0x3e0293ee, v120
	s_and_b64 vcc, s[26:27], s[60:61]
	v_cndmask_b32_e32 v230, v114, v219, vcc
	v_fmamk_f32 v114, v211, 0x420c0000, v126
	v_fmac_f32_e32 v114, 0x3e0293ee, v121
	s_and_b64 vcc, s[26:27], s[62:63]
	v_cndmask_b32_e32 v231, v114, v219, vcc
	v_fmamk_f32 v114, v211, 0x42400000, v126
	v_max3_f32 v0, v130, s4, v131
	v_fmac_f32_e32 v114, 0x3e0293ee, v122
	s_and_b64 vcc, s[26:27], s[64:65]
	v_max3_f32 v0, v0, v132, v133
	v_cndmask_b32_e32 v232, v114, v219, vcc
	v_fmamk_f32 v114, v211, 0x42440000, v126
	v_max3_f32 v0, v0, v134, v135
	v_fmac_f32_e32 v114, 0x3e0293ee, v123
	s_and_b64 vcc, s[26:27], s[66:67]
	v_max3_f32 v0, v0, v136, v137
	v_cndmask_b32_e32 v233, v114, v219, vcc
	v_fmamk_f32 v114, v211, 0x42480000, v126
	v_max3_f32 v0, v0, v227, v229
	v_fmac_f32_e32 v114, 0x3e0293ee, v124
	s_and_b64 vcc, s[26:27], s[68:69]
	v_fmac_f32_e32 v126, 0x424c0000, v211
	v_max3_f32 v0, v0, v230, v231
	v_cndmask_b32_e32 v234, v114, v219, vcc
	v_fmac_f32_e32 v126, 0x3e0293ee, v125
	s_and_b64 vcc, s[26:27], s[70:71]
	v_max3_f32 v0, v0, v232, v233
	v_cndmask_b32_e32 v235, v126, v219, vcc
	v_max3_f32 v0, v0, v234, v235
	v_mov_b32_e32 v114, v0
	s_nop 1
	v_permlane16_swap_b32_e32 v0, v114
	v_max_f32_e32 v114, v114, v114
	v_max_f32_e32 v0, v0, v0
	v_max_f32_e32 v0, v0, v114
	v_mov_b32_e32 v114, v0
	s_nop 1
	v_permlane32_swap_b32_e32 v0, v114
	v_max_f32_e32 v114, v114, v114
	v_max_f32_e32 v0, v0, v0
	v_max_f32_e32 v0, v0, v114
	v_max_f32_e32 v114, v226, v226
	v_max_f32_e32 v228, v114, v0
	ds_read_b64_tr_b16 v[126:127], v162 offset:34816
	ds_read_b64_tr_b16 v[114:115], v162 offset:34848
	ds_read_b64_tr_b16 v[128:129], v162 offset:43520
	ds_read_b64_tr_b16 v[122:123], v162 offset:52224
	ds_read_b64_tr_b16 v[124:125], v162 offset:60928
	ds_read_b64_tr_b16 v[116:117], v162 offset:43552
	ds_read_b64_tr_b16 v[118:119], v162 offset:52256
	ds_read_b64_tr_b16 v[120:121], v162 offset:60960
	v_cmp_gt_f32_e32 vcc, v0, v226
	v_sub_f32_e32 v0, v226, v228
	v_exp_f32_e32 v0, v0
	s_cbranch_vccz .LBB0_894
; __device__ __forceinline__ unsigned pk2(float lo, float hi) { const f32x2 v = {lo, hi}; const bf16x2_n b = __builtin_convertvector(v, bf16x2_n); return __builtin_bit_cast(unsigned, b); }
; #define ATT_LDV(dst_, mt_) do { _Pragma("unroll") for (int e = 0; e < 2; ++e) { const LAS unsigned char* vp = vb_ + e * 17408 + (mt_) * 32; \
;                     const s16x4 a0 = ds_tr16(vp), a1 = ds_tr16(vp + 8704); dst_[e] = (bf16x8){a0[0], a0[1], a0[2], a0[3], a1[0], a1[1], a1[2], a1[3]}; } } while (0)
; #define ATT_PV(src_, mt_) do { _Pragma("unroll") for (int e = 0; e < 2; ++e) O[mt_] = mfma16(src_[e], pf[e], O[mt_]); } while (0)
; #define ATT_SB() __builtin_amdgcn_sched_barrier(0)
; __device__ __forceinline__ void attn_phase(LAS unsigned char* lds, const bf16* PROJ, bf16* MIX, const float* lq1, const float* lk1, const float* lq2, const float* lk2,
;                                            const float* norm_g, float lambda_init, int G, int wave_s) {
;     ...
;                 const float mn = fmaxf(m_run, mx), alpha = __builtin_amdgcn_exp2f(m_run - mn); m_run = mn;
;                 float ps = 0.f;
; #pragma unroll
;                 for (int t16 = 0; t16 < 4; ++t16)
; #pragma unroll
;                     for (int r = 0; r < 4; ++r) { const float pv = __builtin_amdgcn_exp2f(s[t16][r] - mn); s[t16][r] = pv; ps += pv; }
;                 l_part = l_part * alpha + ps;
;                 bf16x8 pf[2];
; #pragma unroll
;                 for (int ks = 0; ks < 2; ++ks) { v4u pw; pw.x = pk2(s[2 * ks][0], s[2 * ks][1]); pw.y = pk2(s[2 * ks][2], s[2 * ks][3]); pw.z = pk2(s[2 * ks + 1][0], s[2 * ks + 1][1]); pw.w = pk2(s[2 * ks + 1][2], s[2 * ks + 1][3]);
;                     pf[ks] = __builtin_bit_cast(bf16x8, pw); }
;                 { bf16x8 va[2], vb[2], vc[2];
;                   ATT_LDV(va, 0); ATT_LDV(vb, 1);
;                   if (resc) {
; #pragma unroll
;                   for (int mt = 0; mt < 16; ++mt) O[mt] = O[mt] * alpha; }
;                   ATT_SB();
;                   ATT_LDV(vc, 2); ATT_PV(va, 0); ATT_SB(); ATT_LDV(va, 3); ATT_PV(vb, 1); ATT_SB(); ATT_LDV(vb, 4); ATT_PV(vc, 2); ATT_SB(); ATT_LDV(vc, 5); ATT_PV(va, 3); ATT_SB();
;                   ATT_LDV(va, 6); ATT_PV(vb, 4); ATT_SB(); ATT_LDV(vb, 7); ATT_PV(vc, 5); ATT_SB(); ATT_LDV(vc, 8); ATT_PV(va, 6); ATT_SB(); ATT_LDV(va, 9); ATT_PV(vb, 7); ATT_SB();
	v_pk_mul_f32 v[64:65], v[64:65], v[0:1] op_sel_hi:[1,0]
	v_pk_mul_f32 v[62:63], v[62:63], v[0:1] op_sel_hi:[1,0]
	v_pk_mul_f32 v[60:61], v[60:61], v[0:1] op_sel_hi:[1,0]
	v_pk_mul_f32 v[58:59], v[58:59], v[0:1] op_sel_hi:[1,0]
	v_pk_mul_f32 v[56:57], v[56:57], v[0:1] op_sel_hi:[1,0]
	v_pk_mul_f32 v[54:55], v[54:55], v[0:1] op_sel_hi:[1,0]
	v_pk_mul_f32 v[52:53], v[52:53], v[0:1] op_sel_hi:[1,0]
	v_pk_mul_f32 v[50:51], v[50:51], v[0:1] op_sel_hi:[1,0]
	v_pk_mul_f32 v[48:49], v[48:49], v[0:1] op_sel_hi:[1,0]
	v_pk_mul_f32 v[46:47], v[46:47], v[0:1] op_sel_hi:[1,0]
	v_pk_mul_f32 v[44:45], v[44:45], v[0:1] op_sel_hi:[1,0]
	v_pk_mul_f32 v[42:43], v[42:43], v[0:1] op_sel_hi:[1,0]
	v_pk_mul_f32 v[40:41], v[40:41], v[0:1] op_sel_hi:[1,0]
	v_pk_mul_f32 v[38:39], v[38:39], v[0:1] op_sel_hi:[1,0]
	v_pk_mul_f32 v[36:37], v[36:37], v[0:1] op_sel_hi:[1,0]
	v_pk_mul_f32 v[34:35], v[34:35], v[0:1] op_sel_hi:[1,0]
	v_pk_mul_f32 v[32:33], v[32:33], v[0:1] op_sel_hi:[1,0]
	v_pk_mul_f32 v[30:31], v[30:31], v[0:1] op_sel_hi:[1,0]
	v_pk_mul_f32 v[28:29], v[28:29], v[0:1] op_sel_hi:[1,0]
	v_pk_mul_f32 v[26:27], v[26:27], v[0:1] op_sel_hi:[1,0]
	v_pk_mul_f32 v[24:25], v[24:25], v[0:1] op_sel_hi:[1,0]
	v_pk_mul_f32 v[22:23], v[22:23], v[0:1] op_sel_hi:[1,0]
	v_pk_mul_f32 v[16:17], v[16:17], v[0:1] op_sel_hi:[1,0]
	v_pk_mul_f32 v[14:15], v[14:15], v[0:1] op_sel_hi:[1,0]
	v_pk_mul_f32 v[20:21], v[20:21], v[0:1] op_sel_hi:[1,0]
	v_pk_mul_f32 v[18:19], v[18:19], v[0:1] op_sel_hi:[1,0]
	v_pk_mul_f32 v[12:13], v[12:13], v[0:1] op_sel_hi:[1,0]
	v_pk_mul_f32 v[10:11], v[10:11], v[0:1] op_sel_hi:[1,0]
	v_pk_mul_f32 v[8:9], v[8:9], v[0:1] op_sel_hi:[1,0]
	v_pk_mul_f32 v[6:7], v[6:7], v[0:1] op_sel_hi:[1,0]
	v_pk_mul_f32 v[4:5], v[4:5], v[0:1] op_sel_hi:[1,0]
	v_pk_mul_f32 v[2:3], v[2:3], v[0:1] op_sel_hi:[1,0]
.LBB0_894:
	v_sub_f32_e32 v130, v130, v228
	v_exp_f32_e32 v130, v130
	v_sub_f32_e32 v131, v131, v228
	v_exp_f32_e32 v131, v131
	v_sub_f32_e32 v132, v132, v228
	v_exp_f32_e32 v132, v132
	v_sub_f32_e32 v133, v133, v228
	v_exp_f32_e32 v133, v133
	v_sub_f32_e32 v134, v134, v228
	v_add_f32_e32 v212, 0, v130
	v_exp_f32_e32 v134, v134
	v_sub_f32_e32 v135, v135, v228
	v_add_f32_e32 v212, v131, v212
	v_exp_f32_e32 v135, v135
	v_sub_f32_e32 v136, v136, v228
	v_add_f32_e32 v212, v132, v212
	v_exp_f32_e32 v136, v136
	v_sub_f32_e32 v137, v137, v228
	v_add_f32_e32 v212, v133, v212
	v_exp_f32_e32 v137, v137
	v_sub_f32_e32 v213, v227, v228
	v_add_f32_e32 v212, v134, v212
	v_exp_f32_e32 v213, v213
	v_sub_f32_e32 v226, v229, v228
	v_add_f32_e32 v212, v135, v212
	v_exp_f32_e32 v226, v226
	v_sub_f32_e32 v227, v230, v228
	v_add_f32_e32 v212, v136, v212
	v_exp_f32_e32 v227, v227
	v_sub_f32_e32 v229, v231, v228
	v_add_f32_e32 v212, v137, v212
	v_exp_f32_e32 v229, v229
	v_sub_f32_e32 v230, v232, v228
	v_add_f32_e32 v212, v213, v212
	v_exp_f32_e32 v230, v230
	v_sub_f32_e32 v231, v233, v228
	v_add_f32_e32 v212, v226, v212
	v_exp_f32_e32 v231, v231
	v_sub_f32_e32 v232, v234, v228
	v_add_f32_e32 v212, v227, v212
	v_exp_f32_e32 v232, v232
	v_sub_f32_e32 v233, v235, v228
	v_add_f32_e32 v212, v229, v212
	v_exp_f32_e32 v233, v233
	v_add_f32_e32 v212, v230, v212
	v_add_f32_e32 v212, v231, v212
	v_add_f32_e32 v212, v232, v212
	v_cvt_pk_bf16_f32 v130, v130, v131
	v_cvt_pk_bf16_f32 v131, v132, v133
	v_cvt_pk_bf16_f32 v132, v134, v135
	v_cvt_pk_bf16_f32 v135, v227, v229
	v_add_f32_e32 v227, v233, v212
	v_fmac_f32_e32 v227, v225, v0
	v_cvt_pk_bf16_f32 v133, v136, v137
	v_cvt_pk_bf16_f32 v134, v213, v226
	v_cvt_pk_bf16_f32 v136, v230, v231
	v_cvt_pk_bf16_f32 v137, v232, v233
	s_waitcnt lgkmcnt(5)
	v_mfma_f32_16x16x32_bf16 v[62:65], v[126:129], v[130:133], v[62:65]
	ds_read_b64_tr_b16 v[126:127], v162 offset:34880
	ds_read_b64_tr_b16 v[128:129], v162 offset:43584
	ds_read_b64_tr_b16 v[230:231], v162 offset:52288
	ds_read_b64_tr_b16 v[232:233], v162 offset:60992
	s_waitcnt lgkmcnt(7)
	v_mfma_f32_16x16x32_bf16 v[62:65], v[122:125], v[134:137], v[62:65]
	s_waitcnt lgkmcnt(6)
	v_mfma_f32_16x16x32_bf16 v[58:61], v[114:117], v[130:133], v[58:61]
	ds_read_b64_tr_b16 v[114:115], v162 offset:34912
	ds_read_b64_tr_b16 v[116:117], v162 offset:43616
	ds_read_b64_tr_b16 v[122:123], v162 offset:52320
	ds_read_b64_tr_b16 v[124:125], v162 offset:61024
	s_waitcnt lgkmcnt(8)
	v_mfma_f32_16x16x32_bf16 v[58:61], v[118:121], v[134:137], v[58:61]
	s_waitcnt lgkmcnt(6)
	v_mfma_f32_16x16x32_bf16 v[54:57], v[126:129], v[130:133], v[54:57]
	ds_read_b64_tr_b16 v[118:119], v162 offset:34944
	ds_read_b64_tr_b16 v[120:121], v162 offset:43648
	ds_read_b64_tr_b16 v[126:127], v162 offset:52352
	ds_read_b64_tr_b16 v[128:129], v162 offset:61056
	s_waitcnt lgkmcnt(8)
	v_mfma_f32_16x16x32_bf16 v[54:57], v[230:233], v[134:137], v[54:57]
	s_waitcnt lgkmcnt(6)
	v_mfma_f32_16x16x32_bf16 v[50:53], v[114:117], v[130:133], v[50:53]
	ds_read_b64_tr_b16 v[114:115], v162 offset:34976
	ds_read_b64_tr_b16 v[116:117], v162 offset:43680
	ds_read_b64_tr_b16 v[230:231], v162 offset:52384
	ds_read_b64_tr_b16 v[232:233], v162 offset:61088
	s_waitcnt lgkmcnt(8)
	v_mfma_f32_16x16x32_bf16 v[50:53], v[122:125], v[134:137], v[50:53]
	s_waitcnt lgkmcnt(6)
	v_mfma_f32_16x16x32_bf16 v[46:49], v[118:121], v[130:133], v[46:49]
	ds_read_b64_tr_b16 v[118:119], v162 offset:35008
	ds_read_b64_tr_b16 v[120:121], v162 offset:43712
	ds_read_b64_tr_b16 v[122:123], v162 offset:52416
	ds_read_b64_tr_b16 v[124:125], v162 offset:61120
	s_waitcnt lgkmcnt(8)
	v_mfma_f32_16x16x32_bf16 v[46:49], v[126:129], v[134:137], v[46:49]
	s_waitcnt lgkmcnt(6)
; #define LAS __attribute__((address_space(3)))
; #define ATT_LDK(dst_, t16_) do { _Pragma("unroll") for (int sk = 0; sk < 4; ++sk) dst_[sk] = *(const LAS bf16x8*)(kb_ + (16 * (t16_) + l15) * 272 + (32 * sk + 8 * q4) * 2); } while (0)
; #define ATT_QK(src_, t16_) do { f32x4 acc = (f32x4){0.f, 0.f, 0.f, 0.f}; _Pragma("unroll") for (int sk = 0; sk < 4; ++sk) acc = mfma16(src_[sk], qf[sk], acc); s[t16_] = acc; } while (0)
; #define ATT_LDV(dst_, mt_) do { _Pragma("unroll") for (int e = 0; e < 2; ++e) { const LAS unsigned char* vp = vb_ + e * 17408 + (mt_) * 32; \
;                     const s16x4 a0 = ds_tr16(vp), a1 = ds_tr16(vp + 8704); dst_[e] = (bf16x8){a0[0], a0[1], a0[2], a0[3], a1[0], a1[1], a1[2], a1[3]}; } } while (0)
; #define ATT_SB() __builtin_amdgcn_sched_barrier(0)
; __device__ __forceinline__ void attn_phase(LAS unsigned char* lds, const bf16* PROJ, bf16* MIX, const float* lq1, const float* lk1, const float* lq2, const float* lk2,
;                                            const float* norm_g, float lambda_init, int G, int wave_s) {
;     ...
;                   ATT_LDV(vc, 2); ATT_PV(va, 0); ATT_SB(); ATT_LDV(va, 3); ATT_PV(vb, 1); ATT_SB(); ATT_LDV(vb, 4); ATT_PV(vc, 2); ATT_SB(); ATT_LDV(vc, 5); ATT_PV(va, 3); ATT_SB();
;                   ATT_LDV(va, 6); ATT_PV(vb, 4); ATT_SB(); ATT_LDV(vb, 7); ATT_PV(vc, 5); ATT_SB(); ATT_LDV(vc, 8); ATT_PV(va, 6); ATT_SB(); ATT_LDV(va, 9); ATT_PV(vb, 7); ATT_SB();
;                   ATT_LDV(vb, 10); ATT_PV(vc, 8); ATT_SB(); ATT_LDV(vc, 11); ATT_PV(va, 9); ATT_SB(); ATT_LDV(va, 12); ATT_PV(vb, 10); ATT_SB(); ATT_LDV(vb, 13); ATT_PV(vc, 11); ATT_SB();
;                   ATT_LDV(vc, 14); ATT_PV(va, 12); ATT_SB(); ATT_LDV(va, 15); ATT_PV(vb, 13); ATT_SB(); ATT_PV(vc, 14); ATT_SB(); ATT_PV(va, 15); ATT_SB();
;                   }
;                 __syncthreads();
;               }
;               if (kt0 + 1 <= qb) { const int kt = kt0 + 1;
;                 if (kt < qb) { ATT_WRITE(0); if (kt + 1 < qb) ATT_LOAD(qb - (kt + 2)); }
;                 const LAS unsigned char* kb_ = Kmine + 69632; const LAS unsigned char* vb_ = vtr0 + 69632;
;                 f32x4 s[4];
;                 { bf16x8 kfa[4], kfb[4];
;                   ATT_LDK(kfa, 0); ATT_LDK(kfb, 1); ATT_SB(); ATT_QK(kfa, 0); ATT_LDK(kfa, 2); ATT_SB(); ATT_QK(kfb, 1); ATT_LDK(kfb, 3); ATT_SB(); ATT_QK(kfa, 2); ATT_QK(kfb, 3); }
	v_mfma_f32_16x16x32_bf16 v[42:45], v[114:117], v[130:133], v[42:45]
	ds_read_b64_tr_b16 v[114:115], v162 offset:35040
	ds_read_b64_tr_b16 v[116:117], v162 offset:43744
	ds_read_b64_tr_b16 v[126:127], v162 offset:52448
	ds_read_b64_tr_b16 v[128:129], v162 offset:61152
	s_waitcnt lgkmcnt(8)
	v_mfma_f32_16x16x32_bf16 v[42:45], v[230:233], v[134:137], v[42:45]
	s_waitcnt lgkmcnt(6)
	v_mfma_f32_16x16x32_bf16 v[38:41], v[118:121], v[130:133], v[38:41]
	ds_read_b64_tr_b16 v[118:119], v162 offset:35072
	ds_read_b64_tr_b16 v[120:121], v162 offset:43776
	ds_read_b64_tr_b16 v[230:231], v162 offset:52480
	ds_read_b64_tr_b16 v[232:233], v162 offset:61184
	s_waitcnt lgkmcnt(8)
	v_mfma_f32_16x16x32_bf16 v[38:41], v[122:125], v[134:137], v[38:41]
	s_waitcnt lgkmcnt(6)
	v_mfma_f32_16x16x32_bf16 v[34:37], v[114:117], v[130:133], v[34:37]
	ds_read_b64_tr_b16 v[114:115], v162 offset:35104
	ds_read_b64_tr_b16 v[116:117], v162 offset:43808
	ds_read_b64_tr_b16 v[122:123], v162 offset:52512
	ds_read_b64_tr_b16 v[124:125], v162 offset:61216
	s_waitcnt lgkmcnt(8)
	v_mfma_f32_16x16x32_bf16 v[34:37], v[126:129], v[134:137], v[34:37]
	s_waitcnt lgkmcnt(6)
	v_mfma_f32_16x16x32_bf16 v[30:33], v[118:121], v[130:133], v[30:33]
	ds_read_b64_tr_b16 v[118:119], v162 offset:35136
	ds_read_b64_tr_b16 v[120:121], v162 offset:43840
	ds_read_b64_tr_b16 v[126:127], v162 offset:52544
	ds_read_b64_tr_b16 v[128:129], v162 offset:61248
	s_waitcnt lgkmcnt(8)
	v_mfma_f32_16x16x32_bf16 v[30:33], v[230:233], v[134:137], v[30:33]
	s_waitcnt lgkmcnt(6)
	v_mfma_f32_16x16x32_bf16 v[26:29], v[114:117], v[130:133], v[26:29]
	ds_read_b64_tr_b16 v[114:115], v162 offset:35168
	ds_read_b64_tr_b16 v[116:117], v162 offset:43872
	ds_read_b64_tr_b16 v[230:231], v162 offset:52576
	ds_read_b64_tr_b16 v[232:233], v162 offset:61280
	s_waitcnt lgkmcnt(8)
	v_mfma_f32_16x16x32_bf16 v[26:29], v[122:125], v[134:137], v[26:29]
	s_waitcnt lgkmcnt(6)
	v_mfma_f32_16x16x32_bf16 v[22:25], v[118:121], v[130:133], v[22:25]
	ds_read_b64_tr_b16 v[118:119], v162 offset:35200
	ds_read_b64_tr_b16 v[120:121], v162 offset:43904
	ds_read_b64_tr_b16 v[122:123], v162 offset:52608
	ds_read_b64_tr_b16 v[124:125], v162 offset:61312
	s_waitcnt lgkmcnt(8)
	v_mfma_f32_16x16x32_bf16 v[22:25], v[126:129], v[134:137], v[22:25]
	s_waitcnt lgkmcnt(6)
	v_mfma_f32_16x16x32_bf16 v[14:17], v[114:117], v[130:133], v[14:17]
	ds_read_b64_tr_b16 v[114:115], v162 offset:35232
	ds_read_b64_tr_b16 v[116:117], v162 offset:43936
	ds_read_b64_tr_b16 v[126:127], v162 offset:52640
	ds_read_b64_tr_b16 v[128:129], v162 offset:61344
	s_waitcnt lgkmcnt(8)
	v_mfma_f32_16x16x32_bf16 v[14:17], v[230:233], v[134:137], v[14:17]
	s_waitcnt lgkmcnt(6)
	v_mfma_f32_16x16x32_bf16 v[18:21], v[118:121], v[130:133], v[18:21]
	ds_read_b64_tr_b16 v[118:119], v162 offset:35264
	ds_read_b64_tr_b16 v[120:121], v162 offset:43968
	ds_read_b64_tr_b16 v[230:231], v162 offset:52672
	ds_read_b64_tr_b16 v[232:233], v162 offset:61376
	s_waitcnt lgkmcnt(8)
	v_mfma_f32_16x16x32_bf16 v[18:21], v[122:125], v[134:137], v[18:21]
	s_waitcnt lgkmcnt(6)
	v_mfma_f32_16x16x32_bf16 v[10:13], v[114:117], v[130:133], v[10:13]
	ds_read_b64_tr_b16 v[114:115], v162 offset:35296
	ds_read_b64_tr_b16 v[116:117], v162 offset:44000
	ds_read_b64_tr_b16 v[122:123], v162 offset:52704
	ds_read_b64_tr_b16 v[124:125], v162 offset:61408
	s_waitcnt lgkmcnt(8)
	v_mfma_f32_16x16x32_bf16 v[10:13], v[126:129], v[134:137], v[10:13]
	s_waitcnt lgkmcnt(6)
	v_mfma_f32_16x16x32_bf16 v[6:9], v[118:121], v[130:133], v[6:9]
	s_waitcnt lgkmcnt(4)
	v_mfma_f32_16x16x32_bf16 v[6:9], v[230:233], v[134:137], v[6:9]
	s_waitcnt lgkmcnt(2)
	v_mfma_f32_16x16x32_bf16 v[2:5], v[114:117], v[130:133], v[2:5]
	s_waitcnt lgkmcnt(0)
	v_mfma_f32_16x16x32_bf16 v[2:5], v[122:125], v[134:137], v[2:5]
	s_andn2_b64 vcc, exec, s[8:9]
	s_waitcnt vmcnt(0)
	s_barrier
	s_cbranch_vccnz .LBB0_887
	s_add_i32 s8, s88, 1
	s_cmp_ge_u32 s8, s86
	s_cbranch_scc1 .LBB0_898
.LBB0_898:
	ds_read_b128 v[114:117], v210
	ds_read_b128 v[118:121], v210 offset:64
	ds_read_b128 v[122:125], v210 offset:128
	ds_read_b128 v[126:129], v210 offset:192
	ds_read_b128 v[130:133], v210 offset:4352
	ds_read_b128 v[134:137], v210 offset:4416
	ds_read_b128 v[230:233], v210 offset:4480
	ds_read_b128 v[234:237], v210 offset:4544
	s_waitcnt lgkmcnt(7)
	v_mfma_f32_16x16x32_bf16 v[114:117], v[114:117], v[74:77], 0
	s_waitcnt lgkmcnt(6)
	v_mfma_f32_16x16x32_bf16 v[114:117], v[118:121], v[66:69], v[114:117]
	s_waitcnt lgkmcnt(5)
	v_mfma_f32_16x16x32_bf16 v[114:117], v[122:125], v[70:73], v[114:117]
	s_waitcnt lgkmcnt(4)
	v_mfma_f32_16x16x32_bf16 v[116:119], v[126:129], v[78:81], v[114:117]
	ds_read_b128 v[120:123], v210 offset:8704
	ds_read_b128 v[124:127], v210 offset:8768
	ds_read_b128 v[238:241], v210 offset:8832
	ds_read_b128 v[242:245], v210 offset:8896
	s_waitcnt lgkmcnt(7)
	v_mfma_f32_16x16x32_bf16 v[128:131], v[130:133], v[74:77], 0
	s_waitcnt lgkmcnt(6)
	v_mfma_f32_16x16x32_bf16 v[128:131], v[134:137], v[66:69], v[128:131]
	s_waitcnt lgkmcnt(5)
	v_mfma_f32_16x16x32_bf16 v[128:131], v[230:233], v[70:73], v[128:131]
	s_waitcnt lgkmcnt(4)
	v_mfma_f32_16x16x32_bf16 v[128:131], v[234:237], v[78:81], v[128:131]
	ds_read_b128 v[132:135], v210 offset:13056
	ds_read_b128 v[230:233], v210 offset:13120
	ds_read_b128 v[234:237], v210 offset:13184
	ds_read_b128 v[246:249], v210 offset:13248
	s_add_i32 s8, s88, 1
	s_cmp_ge_u32 s8, s86
	s_cbranch_scc1 .Lattn_dl2
	s_add_u32 s8, s0, 0xc0000
	s_addc_u32 s9, s1, 0
	s_lshl_b32 s100, s89, 4
	s_mov_b32 m0, s100
	s_nop 0
	global_load_lds_dwordx4 v138, s[8:9]
	s_add_i32 m0, s100, 0x2000
	s_nop 0
	global_load_lds_dwordx4 v139, s[8:9]
	s_add_i32 m0, s100, 0x4000
	s_nop 0
	global_load_lds_dwordx4 v140, s[8:9]
	s_add_i32 m0, s100, 0x6000
	s_nop 0
	global_load_lds_dwordx4 v141, s[8:9]
	s_add_i32 m0, s100, 0x8000
	s_nop 0
	global_load_lds_dwordx4 v142, s[8:9]
	s_add_i32 m0, s100, 0xa000
	s_nop 0
	global_load_lds_dwordx4 v143, s[8:9]
	s_add_i32 m0, s100, 0xc000
	s_nop 0
	global_load_lds_dwordx4 v144, s[8:9]
	s_add_i32 m0, s100, 0xe000
	s_nop 0
	global_load_lds_dwordx4 v145, s[8:9]
	s_cmpk_ge_u32 s89, 0x100
	s_cbranch_scc1 .Lattn_dma_3
	s_add_i32 m0, s100, 0x10000
	s_nop 0
	global_load_lds_dwordx4 v146, s[8:9]
; __device__ __forceinline__ float xor16_max(float v) { const auto r = __builtin_amdgcn_permlane16_swap(__float_as_uint(v), __float_as_uint(v), false, false); return fmaxf(__uint_as_float(r[0]), __uint_as_float(r[1])); }
; __device__ __forceinline__ float xor32_max(float v) { const auto r = __builtin_amdgcn_permlane32_swap(__float_as_uint(v), __float_as_uint(v), false, false); return fmaxf(__uint_as_float(r[0]), __uint_as_float(r[1])); }
; __device__ __forceinline__ void attn_phase(LAS unsigned char* lds, const bf16* PROJ, bf16* MIX, const float* lq1, const float* lk1, const float* lq2, const float* lk2,
;                                            const float* norm_g, float lambda_init, int G, int wave_s) {
;     ...
;                 const int dq = 64 * kt + qloc; const bool diag = (kt == 0);
;                 const float nb = -sl2 * ((float)dq - q4f);
;                 float mx = -1e30f;
; #pragma unroll
;                 for (int t16 = 0; t16 < 4; ++t16)
; #pragma unroll
;                     for (int r = 0; r < 4; ++r) { const int kl = 16 * t16 + 4 * q4 + r; float v = fmaf(s[t16][r], c1, fmaf(sl2, (float)(16 * t16 + r), nb));
;                         if (diag && kl > qloc) v = -1e30f; s[t16][r] = v; mx = fmaxf(mx, v); }
;                 mx = xor32_max(xor16_max(mx));
;                 const bool resc = __builtin_amdgcn_ballot_w64(mx > m_run) != 0ull;
;                 const float mn = fmaxf(m_run, mx), alpha = __builtin_amdgcn_exp2f(m_run - mn); m_run = mn;
;                 float ps = 0.f;
; #pragma unroll
;                 for (int t16 = 0; t16 < 4; ++t16)
; #pragma unroll
;                     for (int r = 0; r < 4; ++r) { const float pv = __builtin_amdgcn_exp2f(s[t16][r] - mn); s[t16][r] = pv; ps += pv; }
;                 l_part = l_part * alpha + ps;
;                 bf16x8 pf[2];
; #pragma unroll
;                 for (int ks = 0; ks < 2; ++ks) { v4u pw; pw.x = pk2(s[2 * ks][0], s[2 * ks][1]); pw.y = pk2(s[2 * ks][2], s[2 * ks][3]); pw.z = pk2(s[2 * ks + 1][0], s[2 * ks + 1][1]); pw.w = pk2(s[2 * ks + 1][2], s[2 * ks + 1][3]);
;                     pf[ks] = __builtin_bit_cast(bf16x8, pw); }
;                 { bf16x8 va[2], vb[2], vc[2];
;                   ATT_LDV(va, 0); ATT_LDV(vb, 1);
;                   if (resc) {
; #pragma unroll
;                   for (int mt = 0; mt < 16; ++mt) O[mt] = O[mt] * alpha; }
.Lattn_dma_3:
.Lattn_dl2:
	s_waitcnt lgkmcnt(7)
	v_mfma_f32_16x16x32_bf16 v[120:123], v[120:123], v[74:77], 0
	v_add_u32_e32 v0, 64, v224
	v_cvt_f32_u32_e32 v0, v0
	v_sub_f32_e32 v0, v0, v166
	s_waitcnt lgkmcnt(3)
	v_mfma_f32_16x16x32_bf16 v[132:135], v[132:135], v[74:77], 0
	v_mul_f32_e64 v114, v0, -v211
	v_fma_f32 v115, 0, v211, v114
	v_fmac_f32_e32 v115, 0x3e0293ee, v116
	v_mfma_f32_16x16x32_bf16 v[120:123], v[124:127], v[66:69], v[120:123]
	v_fma_f32 v116, v0, -v211, v211
	v_fmac_f32_e32 v116, 0x3e0293ee, v117
	v_fma_f32 v117, 2.0, v211, v114
	s_waitcnt lgkmcnt(2)
	v_mfma_f32_16x16x32_bf16 v[132:135], v[230:233], v[66:69], v[132:135]
	v_fmac_f32_e32 v117, 0x3e0293ee, v118
	v_fmamk_f32 v118, v211, 0x40400000, v114
	v_max3_f32 v0, v115, s4, v116
	v_mfma_f32_16x16x32_bf16 v[120:123], v[238:241], v[70:73], v[120:123]
	v_fmac_f32_e32 v118, 0x3e0293ee, v119
	v_fmamk_f32 v119, v211, 0x41800000, v114
	v_max3_f32 v0, v0, v117, v118
	s_waitcnt lgkmcnt(1)
	v_mfma_f32_16x16x32_bf16 v[132:135], v[234:237], v[70:73], v[132:135]
	v_fmac_f32_e32 v119, 0x3e0293ee, v128
	v_fmamk_f32 v225, v211, 0x41980000, v114
	v_fmac_f32_e32 v225, 0x3e0293ee, v131
	v_mfma_f32_16x16x32_bf16 v[122:125], v[242:245], v[78:81], v[120:123]
	v_fmamk_f32 v230, v211, 0x42000000, v114
	v_fmamk_f32 v231, v211, 0x42040000, v114
	v_fmamk_f32 v233, v211, 0x42080000, v114
	v_fmamk_f32 v120, v211, 0x41880000, v114
	s_waitcnt lgkmcnt(0)
	v_mfma_f32_16x16x32_bf16 v[132:135], v[246:249], v[78:81], v[132:135]
	v_fmac_f32_e32 v120, 0x3e0293ee, v129
	v_fmamk_f32 v121, v211, 0x41900000, v114
	v_max3_f32 v0, v0, v119, v120
	v_fmac_f32_e32 v121, 0x3e0293ee, v130
	v_max3_f32 v0, v0, v121, v225
	v_fmac_f32_e32 v230, 0x3e0293ee, v122
	v_fmac_f32_e32 v231, 0x3e0293ee, v123
	v_fmamk_f32 v234, v211, 0x420c0000, v114
	v_max3_f32 v0, v0, v230, v231
	v_fmac_f32_e32 v233, 0x3e0293ee, v124
	v_fmac_f32_e32 v234, 0x3e0293ee, v125
	v_fmamk_f32 v229, v211, 0x42400000, v114
	v_fmamk_f32 v232, v211, 0x42440000, v114
	v_max3_f32 v0, v0, v233, v234
	v_fmac_f32_e32 v229, 0x3e0293ee, v132
	v_fmac_f32_e32 v232, 0x3e0293ee, v133
	v_fmamk_f32 v235, v211, 0x42480000, v114
	v_fmac_f32_e32 v114, 0x424c0000, v211
	v_max3_f32 v0, v0, v229, v232
	v_fmac_f32_e32 v235, 0x3e0293ee, v134
	v_fmac_f32_e32 v114, 0x3e0293ee, v135
	v_max3_f32 v0, v0, v235, v114
	v_mov_b32_e32 v122, v0
	s_nop 1
	v_permlane16_swap_b32_e32 v0, v122
	v_max_f32_e32 v122, v122, v122
	v_max_f32_e32 v0, v0, v0
	v_max_f32_e32 v0, v0, v122
	v_mov_b32_e32 v122, v0
	s_nop 1
	v_permlane32_swap_b32_e32 v0, v122
	v_max_f32_e32 v122, v122, v122
	v_max_f32_e32 v0, v0, v0
	v_max_f32_e32 v0, v0, v122
	v_max_f32_e32 v122, v228, v228
	v_max_f32_e32 v226, v122, v0
	v_add_u32_e32 v122, 0x19800, v162
	v_add_u32_e32 v124, 0x1fe20, v162
	ds_read_b64_tr_b16 v[134:135], v122
	ds_read_b64_tr_b16 v[124:125], v124
	v_add_u32_e32 v122, 0x1ba00, v162
	ds_read_b64_tr_b16 v[136:137], v122
	v_add_u32_e32 v122, 0x1dc00, v162
	ds_read_b64_tr_b16 v[126:127], v122
	v_add_u32_e32 v122, 0x1fe00, v162
	ds_read_b64_tr_b16 v[128:129], v122
	v_add_u32_e32 v122, 0x19820, v162
	ds_read_b64_tr_b16 v[130:131], v122
	v_add_u32_e32 v122, 0x1ba20, v162
	ds_read_b64_tr_b16 v[132:133], v122
	v_add_u32_e32 v122, 0x1dc20, v162
	v_cmp_gt_f32_e32 vcc, v0, v228
	v_sub_f32_e32 v0, v228, v226
	ds_read_b64_tr_b16 v[122:123], v122
	v_exp_f32_e32 v0, v0
	s_cbranch_vccz .LBB0_900
	v_pk_mul_f32 v[64:65], v[64:65], v[0:1] op_sel_hi:[1,0]
	v_pk_mul_f32 v[62:63], v[62:63], v[0:1] op_sel_hi:[1,0]
	v_pk_mul_f32 v[60:61], v[60:61], v[0:1] op_sel_hi:[1,0]
	v_pk_mul_f32 v[58:59], v[58:59], v[0:1] op_sel_hi:[1,0]
	v_pk_mul_f32 v[56:57], v[56:57], v[0:1] op_sel_hi:[1,0]
	v_pk_mul_f32 v[54:55], v[54:55], v[0:1] op_sel_hi:[1,0]
	v_pk_mul_f32 v[52:53], v[52:53], v[0:1] op_sel_hi:[1,0]
	v_pk_mul_f32 v[50:51], v[50:51], v[0:1] op_sel_hi:[1,0]
	v_pk_mul_f32 v[48:49], v[48:49], v[0:1] op_sel_hi:[1,0]
	v_pk_mul_f32 v[46:47], v[46:47], v[0:1] op_sel_hi:[1,0]
	v_pk_mul_f32 v[44:45], v[44:45], v[0:1] op_sel_hi:[1,0]
	v_pk_mul_f32 v[42:43], v[42:43], v[0:1] op_sel_hi:[1,0]
	v_pk_mul_f32 v[40:41], v[40:41], v[0:1] op_sel_hi:[1,0]
	v_pk_mul_f32 v[38:39], v[38:39], v[0:1] op_sel_hi:[1,0]
	v_pk_mul_f32 v[36:37], v[36:37], v[0:1] op_sel_hi:[1,0]
	v_pk_mul_f32 v[34:35], v[34:35], v[0:1] op_sel_hi:[1,0]
	v_pk_mul_f32 v[32:33], v[32:33], v[0:1] op_sel_hi:[1,0]
	v_pk_mul_f32 v[30:31], v[30:31], v[0:1] op_sel_hi:[1,0]
	v_pk_mul_f32 v[28:29], v[28:29], v[0:1] op_sel_hi:[1,0]
	v_pk_mul_f32 v[26:27], v[26:27], v[0:1] op_sel_hi:[1,0]
	v_pk_mul_f32 v[24:25], v[24:25], v[0:1] op_sel_hi:[1,0]
	v_pk_mul_f32 v[22:23], v[22:23], v[0:1] op_sel_hi:[1,0]
	v_pk_mul_f32 v[16:17], v[16:17], v[0:1] op_sel_hi:[1,0]
	v_pk_mul_f32 v[14:15], v[14:15], v[0:1] op_sel_hi:[1,0]
	v_pk_mul_f32 v[20:21], v[20:21], v[0:1] op_sel_hi:[1,0]
	v_pk_mul_f32 v[18:19], v[18:19], v[0:1] op_sel_hi:[1,0]
	v_pk_mul_f32 v[12:13], v[12:13], v[0:1] op_sel_hi:[1,0]
	v_pk_mul_f32 v[10:11], v[10:11], v[0:1] op_sel_hi:[1,0]
	v_pk_mul_f32 v[8:9], v[8:9], v[0:1] op_sel_hi:[1,0]
	v_pk_mul_f32 v[6:7], v[6:7], v[0:1] op_sel_hi:[1,0]
	v_pk_mul_f32 v[4:5], v[4:5], v[0:1] op_sel_hi:[1,0]
	v_pk_mul_f32 v[2:3], v[2:3], v[0:1] op_sel_hi:[1,0]
; __device__ __forceinline__ unsigned pk2(float lo, float hi) { const f32x2 v = {lo, hi}; const bf16x2_n b = __builtin_convertvector(v, bf16x2_n); return __builtin_bit_cast(unsigned, b); }
; #define ATT_LDV(dst_, mt_) do { _Pragma("unroll") for (int e = 0; e < 2; ++e) { const LAS unsigned char* vp = vb_ + e * 17408 + (mt_) * 32; \
;                     const s16x4 a0 = ds_tr16(vp), a1 = ds_tr16(vp + 8704); dst_[e] = (bf16x8){a0[0], a0[1], a0[2], a0[3], a1[0], a1[1], a1[2], a1[3]}; } } while (0)
; #define ATT_PV(src_, mt_) do { _Pragma("unroll") for (int e = 0; e < 2; ++e) O[mt_] = mfma16(src_[e], pf[e], O[mt_]); } while (0)
; #define ATT_SB() __builtin_amdgcn_sched_barrier(0)
; __device__ __forceinline__ void attn_phase(LAS unsigned char* lds, const bf16* PROJ, bf16* MIX, const float* lq1, const float* lk1, const float* lq2, const float* lk2,
;                                            const float* norm_g, float lambda_init, int G, int wave_s) {
;     ...
;                 float ps = 0.f;
; #pragma unroll
;                 for (int t16 = 0; t16 < 4; ++t16)
; #pragma unroll
;                     for (int r = 0; r < 4; ++r) { const float pv = __builtin_amdgcn_exp2f(s[t16][r] - mn); s[t16][r] = pv; ps += pv; }
;                 l_part = l_part * alpha + ps;
;                 bf16x8 pf[2];
; #pragma unroll
;                 for (int ks = 0; ks < 2; ++ks) { v4u pw; pw.x = pk2(s[2 * ks][0], s[2 * ks][1]); pw.y = pk2(s[2 * ks][2], s[2 * ks][3]); pw.z = pk2(s[2 * ks + 1][0], s[2 * ks + 1][1]); pw.w = pk2(s[2 * ks + 1][2], s[2 * ks + 1][3]);
;                     pf[ks] = __builtin_bit_cast(bf16x8, pw); }
;                 { bf16x8 va[2], vb[2], vc[2];
;                   ATT_LDV(va, 0); ATT_LDV(vb, 1);
;                   if (resc) {
; #pragma unroll
;                   for (int mt = 0; mt < 16; ++mt) O[mt] = O[mt] * alpha; }
;                   ATT_SB();
;                   ATT_LDV(vc, 2); ATT_PV(va, 0); ATT_SB(); ATT_LDV(va, 3); ATT_PV(vb, 1); ATT_SB(); ATT_LDV(vb, 4); ATT_PV(vc, 2); ATT_SB(); ATT_LDV(vc, 5); ATT_PV(va, 3); ATT_SB();
;                   ATT_LDV(va, 6); ATT_PV(vb, 4); ATT_SB(); ATT_LDV(vb, 7); ATT_PV(vc, 5); ATT_SB(); ATT_LDV(vc, 8); ATT_PV(va, 6); ATT_SB(); ATT_LDV(va, 9); ATT_PV(vb, 7); ATT_SB();
.LBB0_900:
	v_sub_f32_e32 v115, v115, v226
	v_exp_f32_e32 v115, v115
	v_sub_f32_e32 v116, v116, v226
	v_exp_f32_e32 v116, v116
	v_sub_f32_e32 v117, v117, v226
	v_exp_f32_e32 v117, v117
	v_sub_f32_e32 v118, v118, v226
	v_exp_f32_e32 v118, v118
	v_sub_f32_e32 v119, v119, v226
	v_add_f32_e32 v212, 0, v115
	v_exp_f32_e32 v119, v119
	v_sub_f32_e32 v120, v120, v226
	v_add_f32_e32 v212, v116, v212
	v_exp_f32_e32 v120, v120
	v_sub_f32_e32 v121, v121, v226
	v_add_f32_e32 v212, v117, v212
	v_exp_f32_e32 v121, v121
	v_sub_f32_e32 v213, v225, v226
	v_add_f32_e32 v212, v118, v212
	v_exp_f32_e32 v213, v213
	v_sub_f32_e32 v225, v230, v226
	v_add_f32_e32 v212, v119, v212
	v_exp_f32_e32 v225, v225
	v_sub_f32_e32 v228, v231, v226
	v_add_f32_e32 v212, v120, v212
	v_exp_f32_e32 v228, v228
	v_sub_f32_e32 v230, v233, v226
	v_add_f32_e32 v212, v121, v212
	v_exp_f32_e32 v230, v230
	v_sub_f32_e32 v231, v234, v226
	v_add_f32_e32 v212, v213, v212
	v_exp_f32_e32 v231, v231
	v_sub_f32_e32 v229, v229, v226
	v_add_f32_e32 v212, v225, v212
	v_exp_f32_e32 v229, v229
	v_sub_f32_e32 v232, v232, v226
	v_add_f32_e32 v212, v228, v212
	v_exp_f32_e32 v232, v232
	v_sub_f32_e32 v233, v235, v226
	v_add_f32_e32 v212, v230, v212
	v_exp_f32_e32 v233, v233
	v_sub_f32_e32 v114, v114, v226
	v_add_f32_e32 v212, v231, v212
	v_exp_f32_e32 v234, v114
	v_add_f32_e32 v212, v229, v212
	v_add_f32_e32 v212, v232, v212
	v_add_f32_e32 v212, v233, v212
	v_cvt_pk_bf16_f32 v114, v115, v116
	v_cvt_pk_bf16_f32 v115, v117, v118
	v_cvt_pk_bf16_f32 v118, v225, v228
	v_add_f32_e32 v225, v234, v212
	v_fmac_f32_e32 v225, v227, v0
	v_cvt_pk_bf16_f32 v116, v119, v120
	v_cvt_pk_bf16_f32 v117, v121, v213
	v_cvt_pk_bf16_f32 v119, v230, v231
	v_cvt_pk_bf16_f32 v120, v229, v232
	v_cvt_pk_bf16_f32 v121, v233, v234
	s_waitcnt lgkmcnt(5)
	v_mfma_f32_16x16x32_bf16 v[62:65], v[134:137], v[114:117], v[62:65]
	v_add_u32_e32 v0, 0x19840, v162
	ds_read_b64_tr_b16 v[134:135], v0
	v_add_u32_e32 v0, 0x1ba40, v162
	ds_read_b64_tr_b16 v[136:137], v0
	v_add_u32_e32 v0, 0x1dc40, v162
	ds_read_b64_tr_b16 v[228:229], v0
	v_add_u32_e32 v0, 0x1fe40, v162
	ds_read_b64_tr_b16 v[230:231], v0
	s_waitcnt lgkmcnt(7)
	v_mfma_f32_16x16x32_bf16 v[62:65], v[126:129], v[118:121], v[62:65]
	s_waitcnt lgkmcnt(5)
	v_mfma_f32_16x16x32_bf16 v[58:61], v[130:133], v[114:117], v[58:61]
	v_add_u32_e32 v0, 0x19860, v162
	ds_read_b64_tr_b16 v[126:127], v0
	v_add_u32_e32 v0, 0x1ba60, v162
	ds_read_b64_tr_b16 v[128:129], v0
	v_add_u32_e32 v0, 0x1dc60, v162
	ds_read_b64_tr_b16 v[130:131], v0
	v_add_u32_e32 v0, 0x1fe60, v162
	ds_read_b64_tr_b16 v[132:133], v0
	s_waitcnt lgkmcnt(8)
	v_mfma_f32_16x16x32_bf16 v[58:61], v[122:125], v[118:121], v[58:61]
	s_waitcnt lgkmcnt(6)
	v_mfma_f32_16x16x32_bf16 v[54:57], v[134:137], v[114:117], v[54:57]
	v_add_u32_e32 v0, 0x19880, v162
	ds_read_b64_tr_b16 v[122:123], v0
	v_add_u32_e32 v0, 0x1ba80, v162
	ds_read_b64_tr_b16 v[124:125], v0
	v_add_u32_e32 v0, 0x1dc80, v162
	ds_read_b64_tr_b16 v[134:135], v0
	v_add_u32_e32 v0, 0x1fe80, v162
	ds_read_b64_tr_b16 v[136:137], v0
	s_waitcnt lgkmcnt(8)
	v_mfma_f32_16x16x32_bf16 v[54:57], v[228:231], v[118:121], v[54:57]
	s_waitcnt lgkmcnt(6)
	v_mfma_f32_16x16x32_bf16 v[50:53], v[126:129], v[114:117], v[50:53]
	v_add_u32_e32 v0, 0x198a0, v162
	ds_read_b64_tr_b16 v[126:127], v0
	v_add_u32_e32 v0, 0x1baa0, v162
	ds_read_b64_tr_b16 v[128:129], v0
	v_add_u32_e32 v0, 0x1dca0, v162
	ds_read_b64_tr_b16 v[228:229], v0
	v_add_u32_e32 v0, 0x1fea0, v162
	ds_read_b64_tr_b16 v[230:231], v0
	s_waitcnt lgkmcnt(8)
	v_mfma_f32_16x16x32_bf16 v[50:53], v[130:133], v[118:121], v[50:53]
	s_waitcnt lgkmcnt(6)
; #define ATT_LDV(dst_, mt_) do { _Pragma("unroll") for (int e = 0; e < 2; ++e) { const LAS unsigned char* vp = vb_ + e * 17408 + (mt_) * 32; \
;                     const s16x4 a0 = ds_tr16(vp), a1 = ds_tr16(vp + 8704); dst_[e] = (bf16x8){a0[0], a0[1], a0[2], a0[3], a1[0], a1[1], a1[2], a1[3]}; } } while (0)
; #define ATT_PV(src_, mt_) do { _Pragma("unroll") for (int e = 0; e < 2; ++e) O[mt_] = mfma16(src_[e], pf[e], O[mt_]); } while (0)
; #define ATT_SB() __builtin_amdgcn_sched_barrier(0)
; __device__ __forceinline__ void attn_phase(LAS unsigned char* lds, const bf16* PROJ, bf16* MIX, const float* lq1, const float* lk1, const float* lq2, const float* lk2,
;                                            const float* norm_g, float lambda_init, int G, int wave_s) {
;     ...
;                   ATT_LDV(va, 6); ATT_PV(vb, 4); ATT_SB(); ATT_LDV(vb, 7); ATT_PV(vc, 5); ATT_SB(); ATT_LDV(vc, 8); ATT_PV(va, 6); ATT_SB(); ATT_LDV(va, 9); ATT_PV(vb, 7); ATT_SB();
;                   ATT_LDV(vb, 10); ATT_PV(vc, 8); ATT_SB(); ATT_LDV(vc, 11); ATT_PV(va, 9); ATT_SB(); ATT_LDV(va, 12); ATT_PV(vb, 10); ATT_SB(); ATT_LDV(vb, 13); ATT_PV(vc, 11); ATT_SB();
;                   ATT_LDV(vc, 14); ATT_PV(va, 12); ATT_SB(); ATT_LDV(va, 15); ATT_PV(vb, 13); ATT_SB(); ATT_PV(vc, 14); ATT_SB(); ATT_PV(va, 15); ATT_SB();
;                   }
;                 __syncthreads();
;               }
	v_mfma_f32_16x16x32_bf16 v[46:49], v[122:125], v[114:117], v[46:49]
	v_add_u32_e32 v0, 0x198c0, v162
	ds_read_b64_tr_b16 v[122:123], v0
	v_add_u32_e32 v0, 0x1bac0, v162
	ds_read_b64_tr_b16 v[124:125], v0
	v_add_u32_e32 v0, 0x1dcc0, v162
	ds_read_b64_tr_b16 v[130:131], v0
	v_add_u32_e32 v0, 0x1fec0, v162
	ds_read_b64_tr_b16 v[132:133], v0
	s_waitcnt lgkmcnt(8)
	v_mfma_f32_16x16x32_bf16 v[46:49], v[134:137], v[118:121], v[46:49]
	s_waitcnt lgkmcnt(6)
	v_mfma_f32_16x16x32_bf16 v[42:45], v[126:129], v[114:117], v[42:45]
	v_add_u32_e32 v0, 0x198e0, v162
	ds_read_b64_tr_b16 v[126:127], v0
	v_add_u32_e32 v0, 0x1bae0, v162
	ds_read_b64_tr_b16 v[128:129], v0
	v_add_u32_e32 v0, 0x1dce0, v162
	ds_read_b64_tr_b16 v[134:135], v0
	v_add_u32_e32 v0, 0x1fee0, v162
	ds_read_b64_tr_b16 v[136:137], v0
	s_waitcnt lgkmcnt(8)
	v_mfma_f32_16x16x32_bf16 v[42:45], v[228:231], v[118:121], v[42:45]
	s_waitcnt lgkmcnt(6)
	v_mfma_f32_16x16x32_bf16 v[38:41], v[122:125], v[114:117], v[38:41]
	v_add_u32_e32 v0, 0x19900, v162
	ds_read_b64_tr_b16 v[122:123], v0
	ds_read_b64_tr_b16 v[124:125], v178
	ds_read_b64_tr_b16 v[228:229], v179
	ds_read_b64_tr_b16 v[230:231], v180
	s_waitcnt lgkmcnt(8)
	v_mfma_f32_16x16x32_bf16 v[38:41], v[130:133], v[118:121], v[38:41]
	s_waitcnt lgkmcnt(6)
	v_mfma_f32_16x16x32_bf16 v[34:37], v[126:129], v[114:117], v[34:37]
	ds_read_b64_tr_b16 v[126:127], v181
	ds_read_b64_tr_b16 v[128:129], v182
	ds_read_b64_tr_b16 v[130:131], v183
	ds_read_b64_tr_b16 v[132:133], v184
	s_waitcnt lgkmcnt(8)
	v_mfma_f32_16x16x32_bf16 v[34:37], v[134:137], v[118:121], v[34:37]
	s_waitcnt lgkmcnt(6)
	v_mfma_f32_16x16x32_bf16 v[30:33], v[122:125], v[114:117], v[30:33]
	ds_read_b64_tr_b16 v[122:123], v185
	ds_read_b64_tr_b16 v[124:125], v186
	ds_read_b64_tr_b16 v[134:135], v187
	ds_read_b64_tr_b16 v[136:137], v188
	s_waitcnt lgkmcnt(8)
	v_mfma_f32_16x16x32_bf16 v[30:33], v[228:231], v[118:121], v[30:33]
	s_waitcnt lgkmcnt(6)
	v_mfma_f32_16x16x32_bf16 v[26:29], v[126:129], v[114:117], v[26:29]
	ds_read_b64_tr_b16 v[126:127], v189
	ds_read_b64_tr_b16 v[128:129], v190
	ds_read_b64_tr_b16 v[228:229], v191
	ds_read_b64_tr_b16 v[230:231], v192
	s_waitcnt lgkmcnt(8)
	v_mfma_f32_16x16x32_bf16 v[26:29], v[130:133], v[118:121], v[26:29]
	s_waitcnt lgkmcnt(6)
	v_mfma_f32_16x16x32_bf16 v[22:25], v[122:125], v[114:117], v[22:25]
	ds_read_b64_tr_b16 v[122:123], v193
	ds_read_b64_tr_b16 v[124:125], v194
	ds_read_b64_tr_b16 v[130:131], v195
	ds_read_b64_tr_b16 v[132:133], v196
	s_waitcnt lgkmcnt(8)
	v_mfma_f32_16x16x32_bf16 v[22:25], v[134:137], v[118:121], v[22:25]
	s_waitcnt lgkmcnt(6)
	v_mfma_f32_16x16x32_bf16 v[14:17], v[126:129], v[114:117], v[14:17]
	ds_read_b64_tr_b16 v[126:127], v197
	ds_read_b64_tr_b16 v[128:129], v198
	ds_read_b64_tr_b16 v[134:135], v199
	ds_read_b64_tr_b16 v[136:137], v200
	s_waitcnt lgkmcnt(8)
	v_mfma_f32_16x16x32_bf16 v[14:17], v[228:231], v[118:121], v[14:17]
	s_waitcnt lgkmcnt(6)
	v_mfma_f32_16x16x32_bf16 v[18:21], v[122:125], v[114:117], v[18:21]
	ds_read_b64_tr_b16 v[122:123], v201
	ds_read_b64_tr_b16 v[124:125], v202
	ds_read_b64_tr_b16 v[228:229], v203
	ds_read_b64_tr_b16 v[230:231], v204
	s_waitcnt lgkmcnt(8)
	v_mfma_f32_16x16x32_bf16 v[18:21], v[130:133], v[118:121], v[18:21]
	s_waitcnt lgkmcnt(6)
	v_mfma_f32_16x16x32_bf16 v[10:13], v[126:129], v[114:117], v[10:13]
	ds_read_b64_tr_b16 v[126:127], v205
	ds_read_b64_tr_b16 v[128:129], v206
	ds_read_b64_tr_b16 v[130:131], v207
	ds_read_b64_tr_b16 v[132:133], v208
	s_waitcnt lgkmcnt(8)
	v_mfma_f32_16x16x32_bf16 v[10:13], v[134:137], v[118:121], v[10:13]
	s_waitcnt lgkmcnt(6)
	v_mfma_f32_16x16x32_bf16 v[6:9], v[122:125], v[114:117], v[6:9]
	s_waitcnt lgkmcnt(4)
	v_mfma_f32_16x16x32_bf16 v[6:9], v[228:231], v[118:121], v[6:9]
	s_waitcnt lgkmcnt(2)
	v_mfma_f32_16x16x32_bf16 v[2:5], v[126:129], v[114:117], v[2:5]
	s_waitcnt lgkmcnt(0)
	v_mfma_f32_16x16x32_bf16 v[2:5], v[130:133], v[118:121], v[2:5]
	s_waitcnt vmcnt(0)
	s_barrier
	s_branch .LBB0_888
